# v25: conv loop hand-pipelined (weights hoisted, next-row loads in flight), nt hint on in-proj P stores, chunk-MLP item loads hoisted behind the row loads; chunk-MLP all on WG>=128
# speedup vs baseline: 1.5394x; 1.0191x over previous
.LBB0_92:
	s_cmp_lt_i32 s10, 16
	s_cselect_b64 s[94:95], -1, 0
	s_lshl_b32 s51, s10, 8
	s_add_i32 s51, s51, s2
	v_or_b32_e32 v207, s51, v195
	v_lshl_or_b32 v0, s92, 8, v142
	s_and_b64 vcc, exec, s[94:95]
	s_mov_b64 s[10:11], s[94:95]
	s_cbranch_vccnz .LBB0_111
	s_add_i32 s10, s92, -7
	s_cmp_lt_u32 s10, 2
	s_mov_b64 s[10:11], -1
	s_cbranch_scc0 .LBB0_111
	s_cmp_eq_u32 s92, 7
	s_cselect_b64 s[96:97], -1, 0
	s_bfe_u32 s10, s51, 0x60006
	v_mov_b32_e32 v148, s10
	v_cndmask_b32_e64 v148, v195, v148, s[6:7]
	v_cmp_lt_i32_e32 vcc, v178, v177
	v_cvt_f32_ubyte0_e32 v155, v148
	v_mul_f32_e32 v149, v197, v155
	v_cndmask_b32_e32 v148, v176, v178, vcc
	v_lshlrev_b32_e32 v208, 2, v148
	ds_bpermute_b32 v148, v208, v126
	ds_bpermute_b32 v150, v208, v127
	v_sin_f32_e32 v168, v149
	v_cos_f32_e32 v158, v149
	v_mul_f32_e32 v149, v198, v155
	v_sin_f32_e32 v169, v149
	v_cos_f32_e32 v159, v149
	s_waitcnt lgkmcnt(0)
	v_cndmask_b32_e64 v149, v150, -v150, s[4:5]
	v_cndmask_b32_e64 v148, v148, -v148, s[4:5]
	v_pk_mul_f32 v[148:149], v[168:169], v[148:149]
	ds_bpermute_b32 v152, v208, v129
	v_pk_fma_f32 v[150:151], v[158:159], v[126:127], v[148:149]
	ds_bpermute_b32 v148, v208, v128
	v_mul_f32_e32 v149, v199, v155
	v_sin_f32_e32 v160, v149
	v_cos_f32_e32 v162, v149
	v_mul_f32_e32 v149, v200, v155
	v_sin_f32_e32 v161, v149
	v_cos_f32_e32 v163, v149
	s_waitcnt lgkmcnt(0)
	v_cndmask_b32_e64 v149, v152, -v152, s[4:5]
	v_cndmask_b32_e64 v148, v148, -v148, s[4:5]
	v_pk_mul_f32 v[148:149], v[160:161], v[148:149]
	ds_bpermute_b32 v152, v208, v122
	ds_bpermute_b32 v153, v208, v123
	v_pk_fma_f32 v[166:167], v[162:163], v[128:129], v[148:149]
	v_mul_f32_e32 v148, v201, v155
	v_mul_f32_e32 v149, v202, v155
	v_sin_f32_e32 v156, v148
	v_sin_f32_e32 v157, v149
	v_cos_f32_e32 v148, v148
	v_cos_f32_e32 v149, v149
	s_waitcnt lgkmcnt(0)
	v_cndmask_b32_e64 v153, v153, -v153, s[4:5]
	v_cndmask_b32_e64 v152, v152, -v152, s[4:5]
	v_pk_mul_f32 v[152:153], v[156:157], v[152:153]
	ds_bpermute_b32 v164, v208, v124
	ds_bpermute_b32 v165, v208, v125
	v_pk_fma_f32 v[170:171], v[148:149], v[122:123], v[152:153]
	v_mul_f32_e32 v153, v203, v155
	v_mul_f32_e32 v155, v204, v155
	v_sin_f32_e32 v152, v153
	v_cos_f32_e32 v154, v153
	v_sin_f32_e32 v153, v155
	v_cos_f32_e32 v155, v155
	s_waitcnt lgkmcnt(0)
	v_cndmask_b32_e64 v165, v165, -v165, s[4:5]
	v_cndmask_b32_e64 v164, v164, -v164, s[4:5]
	v_pk_mul_f32 v[164:165], v[152:153], v[164:165]
	s_cmp_lg_u32 s92, 7
	v_pk_fma_f32 v[172:173], v[154:155], v[124:125], v[164:165]
	v_cvt_pk_bf16_f32 v164, v150, v151
	v_mov_b64_e32 v[150:151], s[80:81]
	v_mad_i64_i32 v[150:151], s[10:11], v207, s19, v[150:151]
	v_cvt_pk_bf16_f32 v165, v166, v167
	v_cvt_pk_bf16_f32 v166, v170, v171
	v_cvt_pk_bf16_f32 v167, v172, v173
	v_lshl_add_u64 v[150:151], v[0:1], 1, v[150:151]
	global_store_dwordx4 v[150:151], v[164:167], off nt
	v_mov_b32_e32 v170, v58
	v_mov_b32_e32 v171, v59
	v_mov_b32_e32 v172, v60
	v_mov_b32_e32 v173, v61
	v_mov_b32_e32 v164, v62
	v_mov_b32_e32 v165, v63
	v_mov_b32_e32 v166, v64
	v_mov_b32_e32 v167, v65
	s_cbranch_scc1 .LBB0_96
	ds_bpermute_b32 v164, v208, v62
	ds_bpermute_b32 v165, v208, v63
	ds_bpermute_b32 v166, v208, v64
	v_mul_f32_e32 v162, v162, v64
	v_mul_f32_e32 v154, v154, v60
	s_waitcnt lgkmcnt(0)
	v_cndmask_b32_e64 v164, v164, -v164, s[4:5]
	v_cndmask_b32_e64 v165, v165, -v165, s[4:5]
	v_pk_mul_f32 v[164:165], v[168:169], v[164:165]
	v_cndmask_b32_e64 v166, v166, -v166, s[4:5]
	v_pk_fma_f32 v[164:165], v[158:159], v[62:63], v[164:165]
	ds_bpermute_b32 v158, v208, v58
	ds_bpermute_b32 v159, v208, v59
	v_mul_f32_e32 v166, v160, v166
	ds_bpermute_b32 v160, v208, v65
	v_mov_b32_e32 v168, v65
	s_waitcnt lgkmcnt(0)
	v_cndmask_b32_e64 v158, v158, -v158, s[4:5]
	v_cndmask_b32_e64 v159, v159, -v159, s[4:5]
	v_pk_mul_f32 v[156:157], v[156:157], v[158:159]
	ds_bpermute_b32 v158, v208, v60
	v_cndmask_b32_e64 v169, v160, -v160, s[4:5]
	v_mov_b32_e32 v160, v163
	v_pk_mul_f32 v[160:161], v[160:161], v[168:169]
	v_pk_fma_f32 v[170:171], v[148:149], v[58:59], v[156:157]
	s_waitcnt lgkmcnt(0)
	v_cndmask_b32_e64 v158, v158, -v158, s[4:5]
	v_mul_f32_e32 v158, v152, v158
	ds_bpermute_b32 v152, v208, v61
	v_mov_b32_e32 v163, v160
	v_mov_b32_e32 v167, v161
	v_mov_b32_e32 v160, v61
	v_pk_add_f32 v[166:167], v[162:163], v[166:167]
	s_waitcnt lgkmcnt(0)
	v_cndmask_b32_e64 v161, v152, -v152, s[4:5]
	v_mov_b32_e32 v152, v155
	v_pk_mul_f32 v[152:153], v[152:153], v[160:161]
	s_nop 0
	v_mov_b32_e32 v155, v152
	v_mov_b32_e32 v159, v153
	v_pk_add_f32 v[172:173], v[154:155], v[158:159]
.LBB0_96:
	s_lshr_b32 s22, s51, 6
	v_or_b32_e32 v180, 16, v207
	v_mov_b32_e32 v148, s22
	v_cndmask_b32_e64 v148, v180, v148, s[6:7]
	v_cvt_pk_bf16_f32 v152, v164, v165
	v_cvt_pk_bf16_f32 v153, v166, v167
	v_cvt_pk_bf16_f32 v154, v170, v171
	v_cvt_pk_bf16_f32 v155, v172, v173
	v_and_b32_e32 v148, 63, v148
	global_store_dwordx4 v[150:151], v[152:155], off offset:256 nt
	ds_bpermute_b32 v150, v208, v119
	ds_bpermute_b32 v152, v208, v121
	v_cvt_f32_ubyte0_e32 v155, v148
	ds_bpermute_b32 v148, v208, v118
	v_mul_f32_e32 v149, v197, v155
	v_sin_f32_e32 v168, v149
	v_cos_f32_e32 v158, v149
	v_mul_f32_e32 v149, v198, v155
	v_sin_f32_e32 v169, v149
	v_cos_f32_e32 v159, v149
	s_waitcnt lgkmcnt(0)
	v_cndmask_b32_e64 v149, v150, -v150, s[4:5]
	v_cndmask_b32_e64 v148, v148, -v148, s[4:5]
	v_pk_mul_f32 v[148:149], v[168:169], v[148:149]
	ds_bpermute_b32 v153, v208, v115
	v_pk_fma_f32 v[150:151], v[158:159], v[118:119], v[148:149]
	ds_bpermute_b32 v148, v208, v120
	v_mul_f32_e32 v149, v199, v155
	v_sin_f32_e32 v160, v149
	v_cos_f32_e32 v162, v149
	v_mul_f32_e32 v149, v200, v155
	v_sin_f32_e32 v161, v149
	v_cos_f32_e32 v163, v149
	v_cndmask_b32_e64 v149, v152, -v152, s[4:5]
	s_waitcnt lgkmcnt(0)
	v_cndmask_b32_e64 v148, v148, -v148, s[4:5]
	v_pk_mul_f32 v[148:149], v[160:161], v[148:149]
	ds_bpermute_b32 v152, v208, v114
	v_pk_fma_f32 v[166:167], v[162:163], v[120:121], v[148:149]
	v_mul_f32_e32 v148, v201, v155
	v_mul_f32_e32 v149, v202, v155
	v_sin_f32_e32 v156, v148
	v_sin_f32_e32 v157, v149
	v_cos_f32_e32 v148, v148
	v_cos_f32_e32 v149, v149
	v_cndmask_b32_e64 v153, v153, -v153, s[4:5]
	s_waitcnt lgkmcnt(0)
	v_cndmask_b32_e64 v152, v152, -v152, s[4:5]
	v_pk_mul_f32 v[152:153], v[156:157], v[152:153]
	ds_bpermute_b32 v164, v208, v116
	ds_bpermute_b32 v165, v208, v117
	v_pk_fma_f32 v[170:171], v[148:149], v[114:115], v[152:153]
	v_mul_f32_e32 v153, v203, v155
	v_mul_f32_e32 v155, v204, v155
	v_sin_f32_e32 v152, v153
	v_cos_f32_e32 v154, v153
	v_sin_f32_e32 v153, v155
	v_cos_f32_e32 v155, v155
	s_waitcnt lgkmcnt(0)
	v_cndmask_b32_e64 v165, v165, -v165, s[4:5]
	v_cndmask_b32_e64 v164, v164, -v164, s[4:5]
	v_pk_mul_f32 v[164:165], v[152:153], v[164:165]
	s_andn2_b64 vcc, exec, s[96:97]
	v_pk_fma_f32 v[172:173], v[154:155], v[116:117], v[164:165]
	v_cvt_pk_bf16_f32 v164, v150, v151
	v_mov_b64_e32 v[150:151], s[80:81]
	v_mad_i64_i32 v[150:151], s[10:11], v180, s19, v[150:151]
	v_cvt_pk_bf16_f32 v165, v166, v167
	v_cvt_pk_bf16_f32 v166, v170, v171
	v_cvt_pk_bf16_f32 v167, v172, v173
	v_lshl_add_u64 v[150:151], v[0:1], 1, v[150:151]
	global_store_dwordx4 v[150:151], v[164:167], off nt
	v_mov_b32_e32 v170, v50
	v_mov_b32_e32 v171, v51
	v_cndmask_b32_e64 v164, 0, 1, s[96:97]
	v_cmp_ne_u32_e64 s[10:11], 1, v164
	v_mov_b32_e32 v172, v52
	v_mov_b32_e32 v173, v53
	v_mov_b32_e32 v164, v54
	v_mov_b32_e32 v165, v55
	v_mov_b32_e32 v166, v56
	v_mov_b32_e32 v167, v57
	s_cbranch_vccnz .LBB0_98
	ds_bpermute_b32 v164, v208, v54
	ds_bpermute_b32 v165, v208, v55
	ds_bpermute_b32 v166, v208, v56
	v_mul_f32_e32 v162, v162, v56
	v_mul_f32_e32 v154, v154, v52
	s_waitcnt lgkmcnt(0)
	v_cndmask_b32_e64 v164, v164, -v164, s[4:5]
	v_cndmask_b32_e64 v165, v165, -v165, s[4:5]
	v_pk_mul_f32 v[164:165], v[168:169], v[164:165]
	v_cndmask_b32_e64 v166, v166, -v166, s[4:5]
	v_pk_fma_f32 v[164:165], v[158:159], v[54:55], v[164:165]
	ds_bpermute_b32 v158, v208, v50
	ds_bpermute_b32 v159, v208, v51
	v_mul_f32_e32 v166, v160, v166
	ds_bpermute_b32 v160, v208, v57
	v_mov_b32_e32 v168, v57
	s_waitcnt lgkmcnt(0)
	v_cndmask_b32_e64 v158, v158, -v158, s[4:5]
	v_cndmask_b32_e64 v159, v159, -v159, s[4:5]
	v_pk_mul_f32 v[156:157], v[156:157], v[158:159]
	ds_bpermute_b32 v158, v208, v52
	v_cndmask_b32_e64 v169, v160, -v160, s[4:5]
	v_mov_b32_e32 v160, v163
	v_pk_mul_f32 v[160:161], v[160:161], v[168:169]
	v_pk_fma_f32 v[170:171], v[148:149], v[50:51], v[156:157]
	s_waitcnt lgkmcnt(0)
	v_cndmask_b32_e64 v158, v158, -v158, s[4:5]
	v_mul_f32_e32 v158, v152, v158
	ds_bpermute_b32 v152, v208, v53
	v_mov_b32_e32 v163, v160
	v_mov_b32_e32 v167, v161
	v_mov_b32_e32 v160, v53
	v_pk_add_f32 v[166:167], v[162:163], v[166:167]
	s_waitcnt lgkmcnt(0)
	v_cndmask_b32_e64 v161, v152, -v152, s[4:5]
	v_mov_b32_e32 v152, v155
	v_pk_mul_f32 v[152:153], v[152:153], v[160:161]
	s_nop 0
	v_mov_b32_e32 v155, v152
	v_mov_b32_e32 v159, v153
	v_pk_add_f32 v[172:173], v[154:155], v[158:159]
.LBB0_98:
	v_or_b32_e32 v180, 32, v207
	v_mov_b32_e32 v148, s22
	v_cndmask_b32_e64 v148, v180, v148, s[6:7]
	v_cvt_pk_bf16_f32 v152, v164, v165
	v_cvt_pk_bf16_f32 v153, v166, v167
	v_cvt_pk_bf16_f32 v154, v170, v171
	v_cvt_pk_bf16_f32 v155, v172, v173
	v_and_b32_e32 v148, 63, v148
	global_store_dwordx4 v[150:151], v[152:155], off offset:256 nt
	ds_bpermute_b32 v150, v208, v111
	ds_bpermute_b32 v152, v208, v113
	v_cvt_f32_ubyte0_e32 v155, v148
	ds_bpermute_b32 v148, v208, v110
	v_mul_f32_e32 v149, v197, v155
	v_sin_f32_e32 v168, v149
	v_cos_f32_e32 v158, v149
	v_mul_f32_e32 v149, v198, v155
	v_sin_f32_e32 v169, v149
	v_cos_f32_e32 v159, v149
	s_waitcnt lgkmcnt(0)
	v_cndmask_b32_e64 v149, v150, -v150, s[4:5]
	v_cndmask_b32_e64 v148, v148, -v148, s[4:5]
	v_pk_mul_f32 v[148:149], v[168:169], v[148:149]
	ds_bpermute_b32 v153, v208, v107
	v_pk_fma_f32 v[150:151], v[158:159], v[110:111], v[148:149]
	ds_bpermute_b32 v148, v208, v112
	v_mul_f32_e32 v149, v199, v155
	v_sin_f32_e32 v160, v149
	v_cos_f32_e32 v162, v149
	v_mul_f32_e32 v149, v200, v155
	v_sin_f32_e32 v161, v149
	v_cos_f32_e32 v163, v149
	v_cndmask_b32_e64 v149, v152, -v152, s[4:5]
	s_waitcnt lgkmcnt(0)
	v_cndmask_b32_e64 v148, v148, -v148, s[4:5]
	v_pk_mul_f32 v[148:149], v[160:161], v[148:149]
	ds_bpermute_b32 v152, v208, v106
	v_pk_fma_f32 v[166:167], v[162:163], v[112:113], v[148:149]
	v_mul_f32_e32 v148, v201, v155
	v_mul_f32_e32 v149, v202, v155
	v_sin_f32_e32 v156, v148
	v_sin_f32_e32 v157, v149
	v_cos_f32_e32 v148, v148
	v_cos_f32_e32 v149, v149
	v_cndmask_b32_e64 v153, v153, -v153, s[4:5]
	s_waitcnt lgkmcnt(0)
	v_cndmask_b32_e64 v152, v152, -v152, s[4:5]
	v_pk_mul_f32 v[152:153], v[156:157], v[152:153]
	ds_bpermute_b32 v164, v208, v108
	ds_bpermute_b32 v165, v208, v109
	v_pk_fma_f32 v[170:171], v[148:149], v[106:107], v[152:153]
	v_mul_f32_e32 v153, v203, v155
	v_mul_f32_e32 v155, v204, v155
	v_sin_f32_e32 v152, v153
	v_cos_f32_e32 v154, v153
	v_sin_f32_e32 v153, v155
	v_cos_f32_e32 v155, v155
	s_waitcnt lgkmcnt(0)
	v_cndmask_b32_e64 v165, v165, -v165, s[4:5]
	v_cndmask_b32_e64 v164, v164, -v164, s[4:5]
	v_pk_mul_f32 v[164:165], v[152:153], v[164:165]
	s_and_b64 vcc, exec, s[10:11]
	v_pk_fma_f32 v[172:173], v[154:155], v[108:109], v[164:165]
	v_cvt_pk_bf16_f32 v164, v150, v151
	v_mov_b64_e32 v[150:151], s[80:81]
	v_mad_i64_i32 v[150:151], s[20:21], v180, s19, v[150:151]
	v_cvt_pk_bf16_f32 v165, v166, v167
	v_cvt_pk_bf16_f32 v166, v170, v171
	v_cvt_pk_bf16_f32 v167, v172, v173
	v_lshl_add_u64 v[150:151], v[0:1], 1, v[150:151]
	global_store_dwordx4 v[150:151], v[164:167], off nt
	v_mov_b32_e32 v170, v42
	v_mov_b32_e32 v171, v43
	v_mov_b32_e32 v172, v44
	v_mov_b32_e32 v173, v45
	v_mov_b32_e32 v164, v46
	v_mov_b32_e32 v165, v47
	v_mov_b32_e32 v166, v48
	v_mov_b32_e32 v167, v49
	s_cbranch_vccnz .LBB0_100
	ds_bpermute_b32 v164, v208, v46
	ds_bpermute_b32 v165, v208, v47
	ds_bpermute_b32 v166, v208, v48
	v_mul_f32_e32 v162, v162, v48
	v_mul_f32_e32 v154, v154, v44
	s_waitcnt lgkmcnt(0)
	v_cndmask_b32_e64 v164, v164, -v164, s[4:5]
	v_cndmask_b32_e64 v165, v165, -v165, s[4:5]
	v_pk_mul_f32 v[164:165], v[168:169], v[164:165]
	v_cndmask_b32_e64 v166, v166, -v166, s[4:5]
	v_pk_fma_f32 v[164:165], v[158:159], v[46:47], v[164:165]
	ds_bpermute_b32 v158, v208, v42
	ds_bpermute_b32 v159, v208, v43
	v_mul_f32_e32 v166, v160, v166
	ds_bpermute_b32 v160, v208, v49
	v_mov_b32_e32 v168, v49
	s_waitcnt lgkmcnt(0)
	v_cndmask_b32_e64 v158, v158, -v158, s[4:5]
	v_cndmask_b32_e64 v159, v159, -v159, s[4:5]
	v_pk_mul_f32 v[156:157], v[156:157], v[158:159]
	ds_bpermute_b32 v158, v208, v44
	v_cndmask_b32_e64 v169, v160, -v160, s[4:5]
	v_mov_b32_e32 v160, v163
	v_pk_mul_f32 v[160:161], v[160:161], v[168:169]
	v_pk_fma_f32 v[170:171], v[148:149], v[42:43], v[156:157]
	s_waitcnt lgkmcnt(0)
	v_cndmask_b32_e64 v158, v158, -v158, s[4:5]
	v_mul_f32_e32 v158, v152, v158
	ds_bpermute_b32 v152, v208, v45
	v_mov_b32_e32 v163, v160
	v_mov_b32_e32 v167, v161
	v_mov_b32_e32 v160, v45
	v_pk_add_f32 v[166:167], v[162:163], v[166:167]
	s_waitcnt lgkmcnt(0)
	v_cndmask_b32_e64 v161, v152, -v152, s[4:5]
	v_mov_b32_e32 v152, v155
	v_pk_mul_f32 v[152:153], v[152:153], v[160:161]
	s_nop 0
	v_mov_b32_e32 v155, v152
	v_mov_b32_e32 v159, v153
	v_pk_add_f32 v[172:173], v[154:155], v[158:159]
.LBB0_100:
	v_or_b32_e32 v180, 48, v207
	v_mov_b32_e32 v148, s22
	v_cndmask_b32_e64 v148, v180, v148, s[6:7]
	v_cvt_pk_bf16_f32 v152, v164, v165
	v_cvt_pk_bf16_f32 v153, v166, v167
	v_cvt_pk_bf16_f32 v154, v170, v171
	v_cvt_pk_bf16_f32 v155, v172, v173
	v_and_b32_e32 v148, 63, v148
	global_store_dwordx4 v[150:151], v[152:155], off offset:256 nt
	ds_bpermute_b32 v150, v208, v103
	ds_bpermute_b32 v152, v208, v105
	v_cvt_f32_ubyte0_e32 v155, v148
	ds_bpermute_b32 v148, v208, v102
	v_mul_f32_e32 v149, v197, v155
	v_sin_f32_e32 v168, v149
	v_cos_f32_e32 v158, v149
	v_mul_f32_e32 v149, v198, v155
	v_sin_f32_e32 v169, v149
	v_cos_f32_e32 v159, v149
	s_waitcnt lgkmcnt(0)
	v_cndmask_b32_e64 v149, v150, -v150, s[4:5]
	v_cndmask_b32_e64 v148, v148, -v148, s[4:5]
	v_pk_mul_f32 v[148:149], v[168:169], v[148:149]
	ds_bpermute_b32 v153, v208, v99
	v_pk_fma_f32 v[150:151], v[158:159], v[102:103], v[148:149]
	ds_bpermute_b32 v148, v208, v104
	v_mul_f32_e32 v149, v199, v155
	v_sin_f32_e32 v160, v149
	v_cos_f32_e32 v162, v149
	v_mul_f32_e32 v149, v200, v155
	v_sin_f32_e32 v161, v149
	v_cos_f32_e32 v163, v149
	v_cndmask_b32_e64 v149, v152, -v152, s[4:5]
	s_waitcnt lgkmcnt(0)
	v_cndmask_b32_e64 v148, v148, -v148, s[4:5]
	v_pk_mul_f32 v[148:149], v[160:161], v[148:149]
	ds_bpermute_b32 v152, v208, v98
	v_pk_fma_f32 v[166:167], v[162:163], v[104:105], v[148:149]
	v_mul_f32_e32 v148, v201, v155
	v_mul_f32_e32 v149, v202, v155
	v_sin_f32_e32 v156, v148
	v_sin_f32_e32 v157, v149
	v_cos_f32_e32 v148, v148
	v_cos_f32_e32 v149, v149
	v_cndmask_b32_e64 v153, v153, -v153, s[4:5]
	s_waitcnt lgkmcnt(0)
	v_cndmask_b32_e64 v152, v152, -v152, s[4:5]
	v_pk_mul_f32 v[152:153], v[156:157], v[152:153]
	ds_bpermute_b32 v164, v208, v100
	ds_bpermute_b32 v165, v208, v101
	v_pk_fma_f32 v[170:171], v[148:149], v[98:99], v[152:153]
	v_mul_f32_e32 v153, v203, v155
	v_mul_f32_e32 v155, v204, v155
	v_sin_f32_e32 v152, v153
	v_cos_f32_e32 v154, v153
	v_sin_f32_e32 v153, v155
	v_cos_f32_e32 v155, v155
	s_waitcnt lgkmcnt(0)
	v_cndmask_b32_e64 v165, v165, -v165, s[4:5]
	v_cndmask_b32_e64 v164, v164, -v164, s[4:5]
	v_pk_mul_f32 v[164:165], v[152:153], v[164:165]
	s_and_b64 vcc, exec, s[10:11]
	v_pk_fma_f32 v[172:173], v[154:155], v[100:101], v[164:165]
	v_cvt_pk_bf16_f32 v164, v150, v151
	v_mov_b64_e32 v[150:151], s[80:81]
	v_mad_i64_i32 v[150:151], s[20:21], v180, s19, v[150:151]
	v_cvt_pk_bf16_f32 v165, v166, v167
	v_cvt_pk_bf16_f32 v166, v170, v171
	v_cvt_pk_bf16_f32 v167, v172, v173
	v_lshl_add_u64 v[150:151], v[0:1], 1, v[150:151]
	global_store_dwordx4 v[150:151], v[164:167], off nt
	v_mov_b32_e32 v170, v34
	v_mov_b32_e32 v171, v35
	v_mov_b32_e32 v172, v36
	v_mov_b32_e32 v173, v37
	v_mov_b32_e32 v164, v38
	v_mov_b32_e32 v165, v39
	v_mov_b32_e32 v166, v40
	v_mov_b32_e32 v167, v41
	s_cbranch_vccnz .LBB0_102
	ds_bpermute_b32 v164, v208, v38
	ds_bpermute_b32 v165, v208, v39
	ds_bpermute_b32 v166, v208, v40
	v_mul_f32_e32 v162, v162, v40
	v_mul_f32_e32 v154, v154, v36
	s_waitcnt lgkmcnt(0)
	v_cndmask_b32_e64 v164, v164, -v164, s[4:5]
	v_cndmask_b32_e64 v165, v165, -v165, s[4:5]
	v_pk_mul_f32 v[164:165], v[168:169], v[164:165]
	v_cndmask_b32_e64 v166, v166, -v166, s[4:5]
	v_pk_fma_f32 v[164:165], v[158:159], v[38:39], v[164:165]
	ds_bpermute_b32 v158, v208, v34
	ds_bpermute_b32 v159, v208, v35
	v_mul_f32_e32 v166, v160, v166
	ds_bpermute_b32 v160, v208, v41
	v_mov_b32_e32 v168, v41
	s_waitcnt lgkmcnt(0)
	v_cndmask_b32_e64 v158, v158, -v158, s[4:5]
	v_cndmask_b32_e64 v159, v159, -v159, s[4:5]
	v_pk_mul_f32 v[156:157], v[156:157], v[158:159]
	ds_bpermute_b32 v158, v208, v36
	v_cndmask_b32_e64 v169, v160, -v160, s[4:5]
	v_mov_b32_e32 v160, v163
	v_pk_mul_f32 v[160:161], v[160:161], v[168:169]
	v_pk_fma_f32 v[170:171], v[148:149], v[34:35], v[156:157]
	s_waitcnt lgkmcnt(0)
	v_cndmask_b32_e64 v158, v158, -v158, s[4:5]
	v_mul_f32_e32 v158, v152, v158
	ds_bpermute_b32 v152, v208, v37
	v_mov_b32_e32 v163, v160
	v_mov_b32_e32 v167, v161
	v_mov_b32_e32 v160, v37
	v_pk_add_f32 v[166:167], v[162:163], v[166:167]
	s_waitcnt lgkmcnt(0)
	v_cndmask_b32_e64 v161, v152, -v152, s[4:5]
	v_mov_b32_e32 v152, v155
	v_pk_mul_f32 v[152:153], v[152:153], v[160:161]
	s_nop 0
	v_mov_b32_e32 v155, v152
	v_mov_b32_e32 v159, v153
	v_pk_add_f32 v[172:173], v[154:155], v[158:159]
.LBB0_102:
	v_add_u32_e32 v209, 0x80, v207
	v_bfe_u32 v148, v209, 6, 6
	v_cvt_pk_bf16_f32 v152, v164, v165
	v_cvt_pk_bf16_f32 v153, v166, v167
	v_cvt_pk_bf16_f32 v154, v170, v171
	v_cvt_pk_bf16_f32 v155, v172, v173
	v_cndmask_b32_e64 v148, v195, v148, s[6:7]
	global_store_dwordx4 v[150:151], v[152:155], off offset:256 nt
	ds_bpermute_b32 v150, v208, v95
	ds_bpermute_b32 v152, v208, v97
	v_cvt_f32_ubyte0_e32 v155, v148
	ds_bpermute_b32 v148, v208, v94
	v_mul_f32_e32 v149, v197, v155
	v_sin_f32_e32 v168, v149
	v_cos_f32_e32 v158, v149
	v_mul_f32_e32 v149, v198, v155
	v_sin_f32_e32 v169, v149
	v_cos_f32_e32 v159, v149
	s_waitcnt lgkmcnt(0)
	v_cndmask_b32_e64 v149, v150, -v150, s[4:5]
	v_cndmask_b32_e64 v148, v148, -v148, s[4:5]
	v_pk_mul_f32 v[148:149], v[168:169], v[148:149]
	ds_bpermute_b32 v153, v208, v91
	v_pk_fma_f32 v[150:151], v[158:159], v[94:95], v[148:149]
	ds_bpermute_b32 v148, v208, v96
	v_mul_f32_e32 v149, v199, v155
	v_sin_f32_e32 v160, v149
	v_cos_f32_e32 v162, v149
	v_mul_f32_e32 v149, v200, v155
	v_sin_f32_e32 v161, v149
	v_cos_f32_e32 v163, v149
	v_cndmask_b32_e64 v149, v152, -v152, s[4:5]
	s_waitcnt lgkmcnt(0)
	v_cndmask_b32_e64 v148, v148, -v148, s[4:5]
	v_pk_mul_f32 v[148:149], v[160:161], v[148:149]
	ds_bpermute_b32 v152, v208, v90
	v_pk_fma_f32 v[166:167], v[162:163], v[96:97], v[148:149]
	v_mul_f32_e32 v148, v201, v155
	v_mul_f32_e32 v149, v202, v155
	v_sin_f32_e32 v156, v148
	v_sin_f32_e32 v157, v149
	v_cos_f32_e32 v148, v148
	v_cos_f32_e32 v149, v149
	v_cndmask_b32_e64 v153, v153, -v153, s[4:5]
	s_waitcnt lgkmcnt(0)
	v_cndmask_b32_e64 v152, v152, -v152, s[4:5]
	v_pk_mul_f32 v[152:153], v[156:157], v[152:153]
	ds_bpermute_b32 v164, v208, v92
	ds_bpermute_b32 v165, v208, v93
	v_pk_fma_f32 v[170:171], v[148:149], v[90:91], v[152:153]
	v_mul_f32_e32 v153, v203, v155
	v_mul_f32_e32 v155, v204, v155
	v_sin_f32_e32 v152, v153
	v_cos_f32_e32 v154, v153
	v_sin_f32_e32 v153, v155
	v_cos_f32_e32 v155, v155
	s_waitcnt lgkmcnt(0)
	v_cndmask_b32_e64 v165, v165, -v165, s[4:5]
	v_cndmask_b32_e64 v164, v164, -v164, s[4:5]
	v_pk_mul_f32 v[164:165], v[152:153], v[164:165]
	s_and_b64 vcc, exec, s[10:11]
	v_pk_fma_f32 v[172:173], v[154:155], v[92:93], v[164:165]
	v_cvt_pk_bf16_f32 v164, v150, v151
	v_mov_b64_e32 v[150:151], s[80:81]
	v_mad_i64_i32 v[150:151], s[20:21], v209, s19, v[150:151]
	v_cvt_pk_bf16_f32 v165, v166, v167
	v_cvt_pk_bf16_f32 v166, v170, v171
	v_cvt_pk_bf16_f32 v167, v172, v173
	v_lshl_add_u64 v[150:151], v[0:1], 1, v[150:151]
	global_store_dwordx4 v[150:151], v[164:167], off nt
	v_mov_b32_e32 v170, v26
	v_mov_b32_e32 v171, v27
	v_mov_b32_e32 v172, v28
	v_mov_b32_e32 v173, v29
	v_mov_b32_e32 v164, v30
	v_mov_b32_e32 v165, v31
	v_mov_b32_e32 v166, v32
	v_mov_b32_e32 v167, v33
	s_cbranch_vccnz .LBB0_104
	ds_bpermute_b32 v164, v208, v30
	ds_bpermute_b32 v165, v208, v31
	ds_bpermute_b32 v166, v208, v32
	v_mul_f32_e32 v162, v162, v32
	v_mul_f32_e32 v154, v154, v28
	s_waitcnt lgkmcnt(0)
	v_cndmask_b32_e64 v164, v164, -v164, s[4:5]
	v_cndmask_b32_e64 v165, v165, -v165, s[4:5]
	v_pk_mul_f32 v[164:165], v[168:169], v[164:165]
	v_cndmask_b32_e64 v166, v166, -v166, s[4:5]
	v_pk_fma_f32 v[164:165], v[158:159], v[30:31], v[164:165]
	ds_bpermute_b32 v158, v208, v26
	ds_bpermute_b32 v159, v208, v27
	v_mul_f32_e32 v166, v160, v166
	ds_bpermute_b32 v160, v208, v33
	v_mov_b32_e32 v168, v33
	s_waitcnt lgkmcnt(0)
	v_cndmask_b32_e64 v158, v158, -v158, s[4:5]
	v_cndmask_b32_e64 v159, v159, -v159, s[4:5]
	v_pk_mul_f32 v[156:157], v[156:157], v[158:159]
	ds_bpermute_b32 v158, v208, v28
	v_cndmask_b32_e64 v169, v160, -v160, s[4:5]
	v_mov_b32_e32 v160, v163
	v_pk_mul_f32 v[160:161], v[160:161], v[168:169]
	v_pk_fma_f32 v[170:171], v[148:149], v[26:27], v[156:157]
	s_waitcnt lgkmcnt(0)
	v_cndmask_b32_e64 v158, v158, -v158, s[4:5]
	v_mul_f32_e32 v158, v152, v158
	ds_bpermute_b32 v152, v208, v29
	v_mov_b32_e32 v163, v160
	v_mov_b32_e32 v167, v161
	v_mov_b32_e32 v160, v29
	v_pk_add_f32 v[166:167], v[162:163], v[166:167]
	s_waitcnt lgkmcnt(0)
	v_cndmask_b32_e64 v161, v152, -v152, s[4:5]
	v_mov_b32_e32 v152, v155
	v_pk_mul_f32 v[152:153], v[152:153], v[160:161]
	s_nop 0
	v_mov_b32_e32 v155, v152
	v_mov_b32_e32 v159, v153
	v_pk_add_f32 v[172:173], v[154:155], v[158:159]
.LBB0_104:
	v_lshrrev_b32_e32 v209, 6, v209
	v_add_u32_e32 v180, 0x90, v207
	v_cndmask_b32_e64 v148, v180, v209, s[6:7]
	v_cvt_pk_bf16_f32 v152, v164, v165
	v_cvt_pk_bf16_f32 v153, v166, v167
	v_cvt_pk_bf16_f32 v154, v170, v171
	v_cvt_pk_bf16_f32 v155, v172, v173
	v_and_b32_e32 v148, 63, v148
	global_store_dwordx4 v[150:151], v[152:155], off offset:256 nt
	ds_bpermute_b32 v150, v208, v87
	ds_bpermute_b32 v152, v208, v89
	v_cvt_f32_ubyte0_e32 v155, v148
	ds_bpermute_b32 v148, v208, v86
	v_mul_f32_e32 v149, v197, v155
	v_sin_f32_e32 v168, v149
	v_cos_f32_e32 v158, v149
	v_mul_f32_e32 v149, v198, v155
	v_sin_f32_e32 v169, v149
	v_cos_f32_e32 v159, v149
	s_waitcnt lgkmcnt(0)
	v_cndmask_b32_e64 v149, v150, -v150, s[4:5]
	v_cndmask_b32_e64 v148, v148, -v148, s[4:5]
	v_pk_mul_f32 v[148:149], v[168:169], v[148:149]
	ds_bpermute_b32 v153, v208, v83
	v_pk_fma_f32 v[150:151], v[158:159], v[86:87], v[148:149]
	ds_bpermute_b32 v148, v208, v88
	v_mul_f32_e32 v149, v199, v155
	v_sin_f32_e32 v160, v149
	v_cos_f32_e32 v162, v149
	v_mul_f32_e32 v149, v200, v155
	v_sin_f32_e32 v161, v149
	v_cos_f32_e32 v163, v149
	v_cndmask_b32_e64 v149, v152, -v152, s[4:5]
	s_waitcnt lgkmcnt(0)
	v_cndmask_b32_e64 v148, v148, -v148, s[4:5]
	v_pk_mul_f32 v[148:149], v[160:161], v[148:149]
	ds_bpermute_b32 v152, v208, v82
	v_pk_fma_f32 v[166:167], v[162:163], v[88:89], v[148:149]
	v_mul_f32_e32 v148, v201, v155
	v_mul_f32_e32 v149, v202, v155
	v_sin_f32_e32 v156, v148
	v_sin_f32_e32 v157, v149
	v_cos_f32_e32 v148, v148
	v_cos_f32_e32 v149, v149
	v_cndmask_b32_e64 v153, v153, -v153, s[4:5]
	s_waitcnt lgkmcnt(0)
	v_cndmask_b32_e64 v152, v152, -v152, s[4:5]
	v_pk_mul_f32 v[152:153], v[156:157], v[152:153]
	ds_bpermute_b32 v164, v208, v84
	ds_bpermute_b32 v165, v208, v85
	v_pk_fma_f32 v[170:171], v[148:149], v[82:83], v[152:153]
	v_mul_f32_e32 v153, v203, v155
	v_mul_f32_e32 v155, v204, v155
	v_sin_f32_e32 v152, v153
	v_cos_f32_e32 v154, v153
	v_sin_f32_e32 v153, v155
	v_cos_f32_e32 v155, v155
	s_waitcnt lgkmcnt(0)
	v_cndmask_b32_e64 v165, v165, -v165, s[4:5]
	v_cndmask_b32_e64 v164, v164, -v164, s[4:5]
	v_pk_mul_f32 v[164:165], v[152:153], v[164:165]
	s_and_b64 vcc, exec, s[10:11]
	v_pk_fma_f32 v[172:173], v[154:155], v[84:85], v[164:165]
	v_cvt_pk_bf16_f32 v164, v150, v151
	v_mov_b64_e32 v[150:151], s[80:81]
	v_mad_i64_i32 v[150:151], s[20:21], v180, s19, v[150:151]
	v_cvt_pk_bf16_f32 v165, v166, v167
	v_cvt_pk_bf16_f32 v166, v170, v171
	v_cvt_pk_bf16_f32 v167, v172, v173
	v_lshl_add_u64 v[150:151], v[0:1], 1, v[150:151]
	global_store_dwordx4 v[150:151], v[164:167], off nt
	v_mov_b32_e32 v170, v18
	v_mov_b32_e32 v171, v19
	v_mov_b32_e32 v172, v20
	v_mov_b32_e32 v173, v21
	v_mov_b32_e32 v164, v22
	v_mov_b32_e32 v165, v23
	v_mov_b32_e32 v166, v24
	v_mov_b32_e32 v167, v25
	s_cbranch_vccnz .LBB0_106
	ds_bpermute_b32 v164, v208, v22
	ds_bpermute_b32 v165, v208, v23
	ds_bpermute_b32 v166, v208, v24
	v_mul_f32_e32 v162, v162, v24
	v_mul_f32_e32 v154, v154, v20
	s_waitcnt lgkmcnt(0)
	v_cndmask_b32_e64 v164, v164, -v164, s[4:5]
	v_cndmask_b32_e64 v165, v165, -v165, s[4:5]
	v_pk_mul_f32 v[164:165], v[168:169], v[164:165]
	v_cndmask_b32_e64 v166, v166, -v166, s[4:5]
	v_pk_fma_f32 v[164:165], v[158:159], v[22:23], v[164:165]
	ds_bpermute_b32 v158, v208, v18
	ds_bpermute_b32 v159, v208, v19
	v_mul_f32_e32 v166, v160, v166
	ds_bpermute_b32 v160, v208, v25
	v_mov_b32_e32 v168, v25
	s_waitcnt lgkmcnt(0)
	v_cndmask_b32_e64 v158, v158, -v158, s[4:5]
	v_cndmask_b32_e64 v159, v159, -v159, s[4:5]
	v_pk_mul_f32 v[156:157], v[156:157], v[158:159]
	ds_bpermute_b32 v158, v208, v20
	v_cndmask_b32_e64 v169, v160, -v160, s[4:5]
	v_mov_b32_e32 v160, v163
	v_pk_mul_f32 v[160:161], v[160:161], v[168:169]
	v_pk_fma_f32 v[170:171], v[148:149], v[18:19], v[156:157]
	s_waitcnt lgkmcnt(0)
	v_cndmask_b32_e64 v158, v158, -v158, s[4:5]
	v_mul_f32_e32 v158, v152, v158
	ds_bpermute_b32 v152, v208, v21
	v_mov_b32_e32 v163, v160
	v_mov_b32_e32 v167, v161
	v_mov_b32_e32 v160, v21
	v_pk_add_f32 v[166:167], v[162:163], v[166:167]
	s_waitcnt lgkmcnt(0)
	v_cndmask_b32_e64 v161, v152, -v152, s[4:5]
	v_mov_b32_e32 v152, v155
	v_pk_mul_f32 v[152:153], v[152:153], v[160:161]
	s_nop 0
	v_mov_b32_e32 v155, v152
	v_mov_b32_e32 v159, v153
	v_pk_add_f32 v[172:173], v[154:155], v[158:159]
.LBB0_106:
	v_add_u32_e32 v180, 0xa0, v207
	v_cndmask_b32_e64 v148, v180, v209, s[6:7]
	v_cvt_pk_bf16_f32 v152, v164, v165
	v_cvt_pk_bf16_f32 v153, v166, v167
	v_cvt_pk_bf16_f32 v154, v170, v171
	v_cvt_pk_bf16_f32 v155, v172, v173
	v_and_b32_e32 v148, 63, v148
	global_store_dwordx4 v[150:151], v[152:155], off offset:256 nt
	ds_bpermute_b32 v150, v208, v79
	ds_bpermute_b32 v152, v208, v81
	v_cvt_f32_ubyte0_e32 v155, v148
	ds_bpermute_b32 v148, v208, v78
	v_mul_f32_e32 v149, v197, v155
	v_sin_f32_e32 v168, v149
	v_cos_f32_e32 v158, v149
	v_mul_f32_e32 v149, v198, v155
	v_sin_f32_e32 v169, v149
	v_cos_f32_e32 v159, v149
	s_waitcnt lgkmcnt(0)
	v_cndmask_b32_e64 v149, v150, -v150, s[4:5]
	v_cndmask_b32_e64 v148, v148, -v148, s[4:5]
	v_pk_mul_f32 v[148:149], v[168:169], v[148:149]
	ds_bpermute_b32 v153, v208, v75
	v_pk_fma_f32 v[150:151], v[158:159], v[78:79], v[148:149]
	ds_bpermute_b32 v148, v208, v80
	v_mul_f32_e32 v149, v199, v155
	v_sin_f32_e32 v160, v149
	v_cos_f32_e32 v162, v149
	v_mul_f32_e32 v149, v200, v155
	v_sin_f32_e32 v161, v149
	v_cos_f32_e32 v163, v149
	v_cndmask_b32_e64 v149, v152, -v152, s[4:5]
	s_waitcnt lgkmcnt(0)
	v_cndmask_b32_e64 v148, v148, -v148, s[4:5]
	v_pk_mul_f32 v[148:149], v[160:161], v[148:149]
	ds_bpermute_b32 v152, v208, v74
	v_pk_fma_f32 v[166:167], v[162:163], v[80:81], v[148:149]
	v_mul_f32_e32 v148, v201, v155
	v_mul_f32_e32 v149, v202, v155
	v_sin_f32_e32 v156, v148
	v_sin_f32_e32 v157, v149
	v_cos_f32_e32 v148, v148
	v_cos_f32_e32 v149, v149
	v_cndmask_b32_e64 v153, v153, -v153, s[4:5]
	s_waitcnt lgkmcnt(0)
	v_cndmask_b32_e64 v152, v152, -v152, s[4:5]
	v_pk_mul_f32 v[152:153], v[156:157], v[152:153]
	ds_bpermute_b32 v164, v208, v76
	ds_bpermute_b32 v165, v208, v77
	v_pk_fma_f32 v[170:171], v[148:149], v[74:75], v[152:153]
	v_mul_f32_e32 v153, v203, v155
	v_mul_f32_e32 v155, v204, v155
	v_sin_f32_e32 v152, v153
	v_cos_f32_e32 v154, v153
	v_sin_f32_e32 v153, v155
	v_cos_f32_e32 v155, v155
	s_waitcnt lgkmcnt(0)
	v_cndmask_b32_e64 v165, v165, -v165, s[4:5]
	v_cndmask_b32_e64 v164, v164, -v164, s[4:5]
	v_pk_mul_f32 v[164:165], v[152:153], v[164:165]
	s_and_b64 vcc, exec, s[10:11]
	v_pk_fma_f32 v[172:173], v[154:155], v[76:77], v[164:165]
	v_cvt_pk_bf16_f32 v164, v150, v151
	v_mov_b64_e32 v[150:151], s[80:81]
	v_mad_i64_i32 v[150:151], s[20:21], v180, s19, v[150:151]
	v_cvt_pk_bf16_f32 v165, v166, v167
	v_cvt_pk_bf16_f32 v166, v170, v171
	v_cvt_pk_bf16_f32 v167, v172, v173
	v_lshl_add_u64 v[150:151], v[0:1], 1, v[150:151]
	global_store_dwordx4 v[150:151], v[164:167], off nt
	v_mov_b32_e32 v170, v10
	v_mov_b32_e32 v171, v11
	v_mov_b32_e32 v172, v12
	v_mov_b32_e32 v173, v13
	v_mov_b32_e32 v164, v14
	v_mov_b32_e32 v165, v15
	v_mov_b32_e32 v166, v16
	v_mov_b32_e32 v167, v17
	s_cbranch_vccnz .LBB0_108
	ds_bpermute_b32 v164, v208, v14
	ds_bpermute_b32 v165, v208, v15
	ds_bpermute_b32 v166, v208, v16
	v_mul_f32_e32 v162, v162, v16
	v_mul_f32_e32 v154, v154, v12
	s_waitcnt lgkmcnt(0)
	v_cndmask_b32_e64 v164, v164, -v164, s[4:5]
	v_cndmask_b32_e64 v165, v165, -v165, s[4:5]
	v_pk_mul_f32 v[164:165], v[168:169], v[164:165]
	v_cndmask_b32_e64 v166, v166, -v166, s[4:5]
	v_pk_fma_f32 v[164:165], v[158:159], v[14:15], v[164:165]
	ds_bpermute_b32 v158, v208, v10
	ds_bpermute_b32 v159, v208, v11
	v_mul_f32_e32 v166, v160, v166
	ds_bpermute_b32 v160, v208, v17
	v_mov_b32_e32 v168, v17
	s_waitcnt lgkmcnt(0)
	v_cndmask_b32_e64 v158, v158, -v158, s[4:5]
	v_cndmask_b32_e64 v159, v159, -v159, s[4:5]
	v_pk_mul_f32 v[156:157], v[156:157], v[158:159]
	ds_bpermute_b32 v158, v208, v12
	v_cndmask_b32_e64 v169, v160, -v160, s[4:5]
	v_mov_b32_e32 v160, v163
	v_pk_mul_f32 v[160:161], v[160:161], v[168:169]
	v_pk_fma_f32 v[170:171], v[148:149], v[10:11], v[156:157]
	s_waitcnt lgkmcnt(0)
	v_cndmask_b32_e64 v158, v158, -v158, s[4:5]
	v_mul_f32_e32 v158, v152, v158
	ds_bpermute_b32 v152, v208, v13
	v_mov_b32_e32 v163, v160
	v_mov_b32_e32 v167, v161
	v_mov_b32_e32 v160, v13
	v_pk_add_f32 v[166:167], v[162:163], v[166:167]
	s_waitcnt lgkmcnt(0)
	v_cndmask_b32_e64 v161, v152, -v152, s[4:5]
	v_mov_b32_e32 v152, v155
	v_pk_mul_f32 v[152:153], v[152:153], v[160:161]
	s_nop 0
	v_mov_b32_e32 v155, v152
	v_mov_b32_e32 v159, v153
	v_pk_add_f32 v[172:173], v[154:155], v[158:159]
.LBB0_108:
	v_cvt_pk_bf16_f32 v152, v164, v165
	v_cvt_pk_bf16_f32 v153, v166, v167
	v_cvt_pk_bf16_f32 v154, v170, v171
	v_cvt_pk_bf16_f32 v155, v172, v173
	v_add_u32_e32 v180, 0xb0, v207
	global_store_dwordx4 v[150:151], v[152:155], off offset:256 nt
	v_cndmask_b32_e64 v148, v180, v209, s[6:7]
	ds_bpermute_b32 v150, v208, v71
	v_and_b32_e32 v148, 63, v148
	v_cvt_f32_ubyte0_e32 v157, v148
	v_mul_f32_e32 v149, v197, v157
	v_sin_f32_e32 v172, v149
	v_cos_f32_e32 v162, v149
	v_mul_f32_e32 v149, v198, v157
	v_sin_f32_e32 v173, v149
	v_cos_f32_e32 v163, v149
	s_waitcnt lgkmcnt(0)
	v_cndmask_b32_e64 v149, v150, -v150, s[4:5]
	ds_bpermute_b32 v150, v208, v72
	v_mul_f32_e32 v151, v199, v157
	ds_bpermute_b32 v152, v208, v73
	v_sin_f32_e32 v164, v151
	v_cos_f32_e32 v166, v151
	v_mul_f32_e32 v151, v200, v157
	v_sin_f32_e32 v165, v151
	v_cos_f32_e32 v167, v151
	s_waitcnt lgkmcnt(0)
	v_cndmask_b32_e64 v151, v152, -v152, s[4:5]
	v_cndmask_b32_e64 v150, v150, -v150, s[4:5]
	v_pk_mul_f32 v[150:151], v[164:165], v[150:151]
	ds_bpermute_b32 v152, v208, v66
	ds_bpermute_b32 v153, v208, v67
	v_pk_fma_f32 v[154:155], v[166:167], v[72:73], v[150:151]
	v_mul_f32_e32 v150, v201, v157
	v_mul_f32_e32 v151, v202, v157
	v_sin_f32_e32 v160, v150
	v_sin_f32_e32 v161, v151
	v_cos_f32_e32 v150, v150
	v_cos_f32_e32 v151, v151
	s_waitcnt lgkmcnt(0)
	v_cndmask_b32_e64 v153, v153, -v153, s[4:5]
	v_cndmask_b32_e64 v152, v152, -v152, s[4:5]
	ds_bpermute_b32 v148, v208, v70
	v_pk_mul_f32 v[152:153], v[160:161], v[152:153]
	ds_bpermute_b32 v170, v208, v69
	v_pk_fma_f32 v[168:169], v[150:151], v[66:67], v[152:153]
	ds_bpermute_b32 v152, v208, v68
	v_mul_f32_e32 v153, v203, v157
	v_sin_f32_e32 v156, v153
	v_cos_f32_e32 v158, v153
	v_mul_f32_e32 v153, v204, v157
	v_sin_f32_e32 v157, v153
	v_cos_f32_e32 v159, v153
	s_waitcnt lgkmcnt(0)
	v_cndmask_b32_e64 v148, v148, -v148, s[4:5]
	v_pk_mul_f32 v[148:149], v[172:173], v[148:149]
	v_cndmask_b32_e64 v153, v170, -v170, s[4:5]
	v_cndmask_b32_e64 v152, v152, -v152, s[4:5]
	v_pk_fma_f32 v[148:149], v[162:163], v[70:71], v[148:149]
	v_pk_mul_f32 v[152:153], v[156:157], v[152:153]
	s_and_b64 vcc, exec, s[10:11]
	v_pk_fma_f32 v[170:171], v[158:159], v[68:69], v[152:153]
	v_cvt_pk_bf16_f32 v152, v148, v149
	v_mov_b64_e32 v[148:149], s[80:81]
	v_mad_i64_i32 v[148:149], s[20:21], v180, s19, v[148:149]
	v_cvt_pk_bf16_f32 v153, v154, v155
	v_cvt_pk_bf16_f32 v154, v168, v169
	v_cvt_pk_bf16_f32 v155, v170, v171
	v_lshl_add_u64 v[148:149], v[0:1], 1, v[148:149]
	global_store_dwordx4 v[148:149], v[152:155], off nt
	v_mov_b32_e32 v169, v5
	v_mov_b32_e32 v168, v4
	v_mov_b32_e32 v171, v3
	v_mov_b32_e32 v170, v2
	v_mov_b32_e32 v153, v9
	v_mov_b32_e32 v152, v8
	v_mov_b32_e32 v155, v7
	v_mov_b32_e32 v154, v6
	s_cbranch_vccnz .LBB0_110
	ds_bpermute_b32 v154, v208, v8
	ds_bpermute_b32 v152, v208, v6
	ds_bpermute_b32 v153, v208, v7
	v_mul_f32_e32 v166, v166, v8
	v_mul_f32_e32 v158, v158, v4
	s_waitcnt lgkmcnt(0)
	v_cndmask_b32_e64 v154, v154, -v154, s[4:5]
	v_mul_f32_e32 v168, v164, v154
	ds_bpermute_b32 v154, v208, v9
	v_cndmask_b32_e64 v153, v153, -v153, s[4:5]
	v_cndmask_b32_e64 v152, v152, -v152, s[4:5]
	v_mov_b32_e32 v164, v167
	v_pk_mul_f32 v[152:153], v[172:173], v[152:153]
	s_waitcnt lgkmcnt(0)
	v_cndmask_b32_e64 v155, v154, -v154, s[4:5]
	v_mov_b32_e32 v154, v9
	v_pk_mul_f32 v[154:155], v[164:165], v[154:155]
	v_mov_b32_e32 v164, v5
	v_mov_b32_e32 v167, v154
	v_mov_b32_e32 v169, v155
	v_pk_fma_f32 v[154:155], v[162:163], v[6:7], v[152:153]
	ds_bpermute_b32 v162, v208, v2
	ds_bpermute_b32 v163, v208, v3
	v_pk_add_f32 v[152:153], v[166:167], v[168:169]
	s_waitcnt lgkmcnt(0)
	v_cndmask_b32_e64 v162, v162, -v162, s[4:5]
	v_cndmask_b32_e64 v163, v163, -v163, s[4:5]
	v_pk_mul_f32 v[160:161], v[160:161], v[162:163]
	ds_bpermute_b32 v162, v208, v4
	v_pk_fma_f32 v[170:171], v[150:151], v[2:3], v[160:161]
	s_waitcnt lgkmcnt(0)
	v_cndmask_b32_e64 v162, v162, -v162, s[4:5]
	v_mul_f32_e32 v162, v156, v162
	ds_bpermute_b32 v156, v208, v5
	s_waitcnt lgkmcnt(0)
	v_cndmask_b32_e64 v165, v156, -v156, s[4:5]
	v_mov_b32_e32 v156, v159
	v_pk_mul_f32 v[156:157], v[156:157], v[164:165]
	s_nop 0
	v_mov_b32_e32 v159, v156
	v_mov_b32_e32 v163, v157
	v_pk_add_f32 v[168:169], v[158:159], v[162:163]

.LBB0_111:
	s_and_b64 vcc, exec, s[10:11]
	s_cbranch_vccz .LBB0_113
	v_ashrrev_i32_e32 v149, 31, v0
	v_mov_b32_e32 v148, v0
	v_mov_b64_e32 v[152:153], s[80:81]
	v_mad_i64_i32 v[150:151], s[10:11], v207, s19, v[152:153]
	v_lshlrev_b64 v[154:155], 1, v[148:149]
	v_lshl_add_u64 v[156:157], v[150:151], 0, v[154:155]
	v_cvt_pk_bf16_f32 v148, v126, v127
	v_cvt_pk_bf16_f32 v149, v128, v129
	v_cvt_pk_bf16_f32 v150, v122, v123
	v_cvt_pk_bf16_f32 v151, v124, v125
	global_store_dwordx4 v[156:157], v[148:151], off nt
	v_or_b32_e32 v0, 16, v207
	v_mov_b32_e32 v170, v2
	v_cvt_pk_bf16_f32 v148, v62, v63
	v_cvt_pk_bf16_f32 v149, v64, v65
	v_cvt_pk_bf16_f32 v150, v58, v59
	v_cvt_pk_bf16_f32 v151, v60, v61
	global_store_dwordx4 v[156:157], v[148:151], off offset:256 nt
	v_mov_b32_e32 v171, v3
	v_mov_b32_e32 v168, v4
	v_mad_i64_i32 v[148:149], s[10:11], v0, s19, v[152:153]
	v_lshl_add_u64 v[156:157], v[148:149], 0, v[154:155]
	v_cvt_pk_bf16_f32 v148, v118, v119
	v_cvt_pk_bf16_f32 v149, v120, v121
	v_cvt_pk_bf16_f32 v150, v114, v115
	v_cvt_pk_bf16_f32 v151, v116, v117
	global_store_dwordx4 v[156:157], v[148:151], off nt
	v_or_b32_e32 v0, 32, v207
	v_mov_b32_e32 v169, v5
	v_cvt_pk_bf16_f32 v148, v54, v55
	v_cvt_pk_bf16_f32 v149, v56, v57
	v_cvt_pk_bf16_f32 v150, v50, v51
	v_cvt_pk_bf16_f32 v151, v52, v53
	global_store_dwordx4 v[156:157], v[148:151], off offset:256 nt
	s_nop 1
	v_mad_i64_i32 v[148:149], s[10:11], v0, s19, v[152:153]
	v_lshl_add_u64 v[156:157], v[148:149], 0, v[154:155]
	v_cvt_pk_bf16_f32 v148, v110, v111
	v_cvt_pk_bf16_f32 v149, v112, v113
	v_cvt_pk_bf16_f32 v150, v106, v107
	v_cvt_pk_bf16_f32 v151, v108, v109
	global_store_dwordx4 v[156:157], v[148:151], off nt
	v_or_b32_e32 v0, 48, v207
	s_nop 0
	v_cvt_pk_bf16_f32 v148, v46, v47
	v_cvt_pk_bf16_f32 v149, v48, v49
	v_cvt_pk_bf16_f32 v150, v42, v43
	v_cvt_pk_bf16_f32 v151, v44, v45
	global_store_dwordx4 v[156:157], v[148:151], off offset:256 nt
	s_nop 1
	v_mad_i64_i32 v[148:149], s[10:11], v0, s19, v[152:153]
	v_lshl_add_u64 v[156:157], v[148:149], 0, v[154:155]
	v_cvt_pk_bf16_f32 v148, v102, v103
	v_cvt_pk_bf16_f32 v149, v104, v105
	v_cvt_pk_bf16_f32 v150, v98, v99
	v_cvt_pk_bf16_f32 v151, v100, v101
	global_store_dwordx4 v[156:157], v[148:151], off nt
	v_add_u32_e32 v0, 0x80, v207
	s_nop 0
	v_cvt_pk_bf16_f32 v148, v38, v39
	v_cvt_pk_bf16_f32 v149, v40, v41
	v_cvt_pk_bf16_f32 v150, v34, v35
	v_cvt_pk_bf16_f32 v151, v36, v37
	global_store_dwordx4 v[156:157], v[148:151], off offset:256 nt
	s_nop 1
	v_mad_i64_i32 v[148:149], s[10:11], v0, s19, v[152:153]
	v_lshl_add_u64 v[156:157], v[148:149], 0, v[154:155]
	v_cvt_pk_bf16_f32 v148, v94, v95
	v_cvt_pk_bf16_f32 v149, v96, v97
	v_cvt_pk_bf16_f32 v150, v90, v91
	v_cvt_pk_bf16_f32 v151, v92, v93
	global_store_dwordx4 v[156:157], v[148:151], off nt
	v_add_u32_e32 v0, 0x90, v207
	s_nop 0
	v_cvt_pk_bf16_f32 v148, v30, v31
	v_cvt_pk_bf16_f32 v149, v32, v33
	v_cvt_pk_bf16_f32 v150, v26, v27
	v_cvt_pk_bf16_f32 v151, v28, v29
	global_store_dwordx4 v[156:157], v[148:151], off offset:256 nt
	s_nop 1
	v_mad_i64_i32 v[148:149], s[10:11], v0, s19, v[152:153]
	v_lshl_add_u64 v[156:157], v[148:149], 0, v[154:155]
	v_cvt_pk_bf16_f32 v148, v86, v87
	v_cvt_pk_bf16_f32 v149, v88, v89
	v_cvt_pk_bf16_f32 v150, v82, v83
	v_cvt_pk_bf16_f32 v151, v84, v85
	global_store_dwordx4 v[156:157], v[148:151], off nt
	v_add_u32_e32 v0, 0xa0, v207
	s_nop 0
	v_cvt_pk_bf16_f32 v148, v22, v23
	v_cvt_pk_bf16_f32 v149, v24, v25
	v_cvt_pk_bf16_f32 v150, v18, v19
	v_cvt_pk_bf16_f32 v151, v20, v21
	global_store_dwordx4 v[156:157], v[148:151], off offset:256 nt
	s_nop 1
	v_mad_i64_i32 v[148:149], s[10:11], v0, s19, v[152:153]
	v_lshl_add_u64 v[156:157], v[148:149], 0, v[154:155]
	v_cvt_pk_bf16_f32 v148, v78, v79
	v_cvt_pk_bf16_f32 v149, v80, v81
	v_cvt_pk_bf16_f32 v150, v74, v75
	v_cvt_pk_bf16_f32 v151, v76, v77
	global_store_dwordx4 v[156:157], v[148:151], off nt
	v_add_u32_e32 v0, 0xb0, v207
	s_nop 0
	v_cvt_pk_bf16_f32 v148, v14, v15
	v_cvt_pk_bf16_f32 v149, v16, v17
	v_cvt_pk_bf16_f32 v150, v10, v11
	v_cvt_pk_bf16_f32 v151, v12, v13
	global_store_dwordx4 v[156:157], v[148:151], off offset:256 nt
	s_nop 1
	v_mad_i64_i32 v[148:149], s[10:11], v0, s19, v[152:153]
	v_lshl_add_u64 v[148:149], v[148:149], 0, v[154:155]
	v_cvt_pk_bf16_f32 v150, v70, v71
	v_cvt_pk_bf16_f32 v151, v72, v73
	v_cvt_pk_bf16_f32 v152, v66, v67
	v_cvt_pk_bf16_f32 v153, v68, v69
	global_store_dwordx4 v[148:149], v[150:153], off nt
	v_mov_b32_e32 v154, v6
	v_mov_b32_e32 v155, v7
	v_mov_b32_e32 v152, v8
	v_mov_b32_e32 v153, v9
.LBB0_113:
	v_cvt_pk_bf16_f32 v150, v154, v155
	v_cvt_pk_bf16_f32 v151, v152, v153
	v_cvt_pk_bf16_f32 v152, v170, v171
	v_cvt_pk_bf16_f32 v153, v168, v169
	s_andn2_b64 vcc, exec, s[94:95]
	s_mov_b64 s[10:11], -1
	global_store_dwordx4 v[148:149], v[150:153], off offset:256 nt
	s_cbranch_vccnz .LBB0_120
	s_cmp_lt_i32 s92, 11
	s_cbranch_scc1 .LBB0_116
	s_cmp_lt_i32 s92, 13
	s_cselect_b64 s[10:11], -1, 0
	s_cbranch_execz .LBB0_117
	s_branch .LBB0_118

.LBB0_118:
	s_andn2_b64 vcc, exec, s[10:11]
	s_mov_b64 s[10:11], 0
	s_cbranch_vccnz .LBB0_120
	s_cmp_eq_u32 s92, 11
	s_mov_b32 s10, 0x1000000
	s_cselect_b32 s10, s10, 0x1400000
	s_cmp_eq_u32 s92, 8
	s_cselect_b32 s10, 0xc00000, s10
	s_cselect_b32 s20, 7, 8
	s_lshl_b32 s10, s10, 2
	s_add_u32 s10, s76, s10
	s_addc_u32 s11, s77, 0
	s_add_u32 s21, s10, 0x200
	s_addc_u32 s22, s11, 0
	s_cmp_eq_u32 s92, 8
	s_cselect_b32 s23, s50, s22
	s_cselect_b32 s22, s49, s21
	s_lshr_b32 s21, s51, 6
	s_and_b32 s21, s21, 0xfffffc
	v_and_b32_e32 v0, 0xcf, v207
	s_or_b32 s21, s21, s34
	v_lshl_or_b32 v148, s21, 8, v0
	v_ashrrev_i32_e32 v149, 31, v148
	v_lshlrev_b64 v[150:151], s20, v[148:149]
	v_lshl_add_u64 v[150:151], v[150:151], 0, v[142:143]
	v_lshlrev_b64 v[150:151], 2, v[150:151]
	v_lshl_add_u64 v[152:153], s[10:11], 0, v[150:151]
	v_lshl_add_u64 v[150:151], s[22:23], 0, v[150:151]
	global_store_dwordx4 v[152:153], v[126:129], off nt
	global_store_dwordx4 v[152:153], v[122:125], off offset:16 nt
	global_store_dwordx4 v[150:151], v[62:65], off nt
	global_store_dwordx4 v[150:151], v[58:61], off offset:16 nt
	v_or_b32_e32 v150, 16, v148
	v_ashrrev_i32_e32 v151, 31, v150
	v_lshlrev_b64 v[150:151], s20, v[150:151]
	v_lshl_add_u64 v[150:151], v[150:151], 0, v[142:143]
	v_lshlrev_b64 v[150:151], 2, v[150:151]
	v_lshl_add_u64 v[152:153], s[10:11], 0, v[150:151]
	v_lshl_add_u64 v[150:151], s[22:23], 0, v[150:151]
	global_store_dwordx4 v[152:153], v[118:121], off nt
	global_store_dwordx4 v[152:153], v[114:117], off offset:16 nt
	global_store_dwordx4 v[150:151], v[54:57], off nt
	global_store_dwordx4 v[150:151], v[50:53], off offset:16 nt
	v_or_b32_e32 v150, 32, v148
	v_ashrrev_i32_e32 v151, 31, v150
	v_or_b32_e32 v148, 48, v148
	v_lshlrev_b64 v[150:151], s20, v[150:151]
	v_ashrrev_i32_e32 v149, 31, v148
	v_lshl_add_u64 v[150:151], v[150:151], 0, v[142:143]
	v_lshlrev_b64 v[148:149], s20, v[148:149]
	v_lshlrev_b64 v[150:151], 2, v[150:151]
	v_lshl_add_u64 v[148:149], v[148:149], 0, v[142:143]
	v_lshl_add_u64 v[152:153], s[10:11], 0, v[150:151]
	v_lshl_add_u64 v[150:151], s[22:23], 0, v[150:151]
	v_lshlrev_b64 v[148:149], 2, v[148:149]
	global_store_dwordx4 v[152:153], v[110:113], off nt
	global_store_dwordx4 v[152:153], v[106:109], off offset:16 nt
	global_store_dwordx4 v[150:151], v[46:49], off nt
	global_store_dwordx4 v[150:151], v[42:45], off offset:16 nt
	v_lshl_add_u64 v[150:151], s[10:11], 0, v[148:149]
	v_lshl_add_u64 v[148:149], s[22:23], 0, v[148:149]
	v_add_u32_e32 v0, 0x80, v207
	global_store_dwordx4 v[150:151], v[102:105], off nt
	global_store_dwordx4 v[150:151], v[98:101], off offset:16 nt
	global_store_dwordx4 v[148:149], v[38:41], off nt
	global_store_dwordx4 v[148:149], v[34:37], off offset:16 nt
	v_and_b32_e32 v148, 0xcf, v0
	v_lshrrev_b32_e32 v0, 6, v0
	v_and_b32_e32 v0, 0xfffffc, v0
	v_or_b32_e32 v0, s34, v0
	v_lshl_or_b32 v148, v0, 8, v148
	v_ashrrev_i32_e32 v149, 31, v148
	v_lshlrev_b64 v[150:151], s20, v[148:149]
	v_lshl_add_u64 v[150:151], v[150:151], 0, v[142:143]
	v_lshlrev_b64 v[150:151], 2, v[150:151]
	v_lshl_add_u64 v[152:153], s[10:11], 0, v[150:151]
	v_lshl_add_u64 v[150:151], s[22:23], 0, v[150:151]
	global_store_dwordx4 v[152:153], v[94:97], off nt
	global_store_dwordx4 v[152:153], v[90:93], off offset:16 nt
	global_store_dwordx4 v[150:151], v[30:33], off nt
	global_store_dwordx4 v[150:151], v[26:29], off offset:16 nt
	v_or_b32_e32 v150, 16, v148
	v_ashrrev_i32_e32 v151, 31, v150
	v_lshlrev_b64 v[150:151], s20, v[150:151]
	v_lshl_add_u64 v[150:151], v[150:151], 0, v[142:143]
	v_lshlrev_b64 v[150:151], 2, v[150:151]
	v_lshl_add_u64 v[152:153], s[10:11], 0, v[150:151]
	v_lshl_add_u64 v[150:151], s[22:23], 0, v[150:151]
	global_store_dwordx4 v[152:153], v[86:89], off nt
	global_store_dwordx4 v[152:153], v[82:85], off offset:16 nt
	global_store_dwordx4 v[150:151], v[22:25], off nt
	global_store_dwordx4 v[150:151], v[18:21], off offset:16 nt
	v_or_b32_e32 v150, 32, v148
	v_ashrrev_i32_e32 v151, 31, v150
	v_or_b32_e32 v148, 48, v148
	v_lshlrev_b64 v[150:151], s20, v[150:151]
	v_ashrrev_i32_e32 v149, 31, v148
	v_lshl_add_u64 v[150:151], v[150:151], 0, v[142:143]
	v_lshlrev_b64 v[148:149], s20, v[148:149]
	v_lshlrev_b64 v[150:151], 2, v[150:151]
	v_lshl_add_u64 v[148:149], v[148:149], 0, v[142:143]
	v_lshl_add_u64 v[152:153], s[10:11], 0, v[150:151]
	v_lshl_add_u64 v[150:151], s[22:23], 0, v[150:151]
	v_lshlrev_b64 v[148:149], 2, v[148:149]
	global_store_dwordx4 v[152:153], v[78:81], off nt
	global_store_dwordx4 v[152:153], v[74:77], off offset:16 nt
	global_store_dwordx4 v[150:151], v[14:17], off nt
	global_store_dwordx4 v[150:151], v[10:13], off offset:16 nt
	v_lshl_add_u64 v[150:151], s[10:11], 0, v[148:149]
	v_lshl_add_u64 v[148:149], s[22:23], 0, v[148:149]
	global_store_dwordx4 v[150:151], v[70:73], off nt
	global_store_dwordx4 v[150:151], v[66:69], off offset:16 nt
	global_store_dwordx4 v[148:149], v[6:9], off nt
	global_store_dwordx4 v[148:149], v[2:5], off offset:16 nt
	s_mov_b64 s[10:11], -1

.LBB0_162:
	s_andn2_b64 vcc, exec, s[6:7]
	s_cbranch_vccnz .LBB0_164
	s_cmpk_lt_i32 s58, 0x80
	s_cselect_b32 s0, 0, 3
.LBB0_164:
	s_add_u32 s6, s76, 0x3d00000
	s_addc_u32 s7, s77, 0
	s_add_u32 s8, s76, 0x9100000
	v_ashrrev_i32_e32 v101, 6, v100
	v_bfe_u32 v125, v100, 5, 1
	s_addc_u32 s9, s77, 0
	v_and_b32_e32 v124, 31, v100
	s_cmp_lt_i32 s0, 1
	v_lshlrev_b32_e32 v82, 4, v100
	v_lshlrev_b32_e32 v70, 5, v101
	v_lshlrev_b32_e32 v98, 4, v125
	s_cbranch_scc1 .LBB0_169
	v_cmp_lt_i32_e32 vcc, v183, v177
	s_lshl_b32 s1, s34, 18
	v_ashrrev_i32_e32 v30, 2, v100
	v_cndmask_b32_e32 v0, v176, v183, vcc
	v_cmp_lt_i32_e32 vcc, v182, v177
	v_lshlrev_b32_e32 v31, 2, v0
	s_add_u32 s10, s10, s1
	v_cndmask_b32_e32 v0, v176, v182, vcc
	v_lshlrev_b32_e32 v32, 2, v0
	v_and_b32_e32 v0, 0xffffffe0, v30
	s_addc_u32 s11, s11, 0
	v_ashrrev_i32_e32 v19, 31, v0
	v_or_b32_e32 v18, v0, v124
	v_lshlrev_b32_e32 v0, 5, v125
	v_lshl_add_u64 v[20:21], s[10:11], 0, v[0:1]
	v_and_b32_e32 v0, 32, v70
	s_lshl_b32 s30, s34, 9
	v_or_b32_e32 v3, v0, v124
	s_lshl_b64 s[12:13], s[30:31], 2
	v_and_b32_e32 v2, 48, v82
	v_mul_u32_u24_e32 v3, 0x110, v3
	s_add_u32 s4, s4, s12
	v_add3_u32 v33, 0, v3, v98
	v_lshl_or_b32 v4, v125, 2, v0
	v_mul_u32_u24_e32 v0, 0x110, v2
	v_lshlrev_b32_e32 v3, 1, v30
	s_addc_u32 s5, s5, s13
	s_mul_i32 s1, s58, 0
	s_add_i32 s2, s58, 0xffffff80
	s_mul_i32 s2, s2, 3
	s_addk_i32 s2, 0x0
	s_cmpk_lt_i32 s58, 0x80
	s_cselect_b32 s1, s1, s2
	s_mov_b32 s2, 0
	v_add3_u32 v34, 0, v0, v3
	v_lshlrev_b32_e32 v0, 1, v2
	v_lshlrev_b32_e32 v22, 1, v4
	s_branch .LBB0_167
.LBB0_166:
	s_lshl_b32 s10, s11, 5
	s_and_b32 s10, s10, 0xffffff80
	v_add_u32_e32 v2, s10, v30
	v_mov_b64_e32 v[26:27], s[6:7]
	s_lshl_b32 s11, s11, 7
	v_mad_i64_i32 v[2:3], s[12:13], v2, s19, v[26:27]
	s_and_b32 s30, s11, 0x180
	v_lshl_add_u64 v[2:3], v[2:3], 0, s[30:31]
	v_lshl_add_u64 v[6:7], v[2:3], 0, v[0:1]
	global_load_dwordx4 v[2:5], v[6:7], off offset:528
	s_nop 0
	global_load_dwordx4 v[6:9], v[6:7], off offset:512
	v_lshl_add_u64 v[162:163], v[18:19], 0, s[30:31]
	v_lshlrev_b64 v[162:163], 9, v[162:163]
	v_lshl_add_u64 v[162:163], v[20:21], 0, v[162:163]
	global_load_dwordx4 v[196:199], v[162:163], off
	global_load_dwordx4 v[200:203], v[162:163], off offset:16
	global_load_dwordx4 v[204:207], v[162:163], off offset:64
	global_load_dwordx4 v[208:211], v[162:163], off offset:80
	global_load_dwordx4 v[212:215], v[162:163], off offset:128
	global_load_dwordx4 v[216:219], v[162:163], off offset:144
	global_load_dwordx4 v[220:223], v[162:163], off offset:192
	global_load_dwordx4 v[224:227], v[162:163], off offset:208
	global_load_dwordx4 v[228:231], v[162:163], off offset:256
	global_load_dwordx4 v[232:235], v[162:163], off offset:272
	global_load_dwordx4 v[236:239], v[162:163], off offset:320
	global_load_dwordx4 v[240:243], v[162:163], off offset:336
	global_load_dwordx4 v[244:247], v[162:163], off offset:384
	global_load_dwordx4 v[248:251], v[162:163], off offset:400
	global_load_dwordx4 v[48:51], v[162:163], off offset:448
	global_load_dwordx4 v[52:55], v[162:163], off offset:464
	v_add_u32_e32 v252, s30, v18
	v_ashrrev_i32_e32 v253, 31, v252
	v_lshl_add_u64 v[252:253], v[252:253], 2, s[4:5]
	global_load_dword v68, v[252:253], off
	v_add_u32_e32 v164, s10, v18
	v_mov_b64_e32 v[56:57], s[6:7]
	v_mov_b32_e32 v58, v22
	v_mov_b32_e32 v59, v1
	v_mad_i64_i32 v[164:165], s[12:13], v164, s19, v[56:57]
	v_lshl_add_u64 v[164:165], v[164:165], 0, s[30:31]
	v_lshl_add_u64 v[164:165], v[164:165], 0, v[58:59]
	global_load_dwordx2 v[60:61], v[164:165], off
	global_load_dwordx2 v[166:167], v[164:165], off offset:1024
	global_load_dwordx2 v[62:63], v[164:165], off offset:16
	global_load_dwordx2 v[168:169], v[164:165], off offset:1040
	global_load_dwordx2 v[64:65], v[164:165], off offset:32
	global_load_dwordx2 v[170:171], v[164:165], off offset:1056
	global_load_dwordx2 v[66:67], v[164:165], off offset:48
	global_load_dwordx2 v[172:173], v[164:165], off offset:1072
	s_add_i32 s2, s2, 1
	s_add_i32 s1, s1, 1
	s_add_i32 s0, s0, -1
	s_cmp_eq_u32 s0, 0
	s_waitcnt vmcnt(26)
	v_lshlrev_b32_e32 v42, 16, v2
	s_waitcnt vmcnt(25)
	v_lshlrev_b32_e32 v16, 16, v6
	v_and_b32_e32 v17, 0xffff0000, v6
	v_pk_mul_f32 v[24:25], v[16:17], v[16:17]
	v_lshlrev_b32_e32 v6, 16, v7
	v_and_b32_e32 v7, 0xffff0000, v7
	v_pk_mul_f32 v[28:29], v[6:7], v[6:7]
	v_add_f32_e32 v23, v24, v25
	v_lshlrev_b32_e32 v36, 16, v8
	v_and_b32_e32 v37, 0xffff0000, v8
	v_add_f32_e32 v23, v28, v23
	v_pk_mul_f32 v[38:39], v[36:37], v[36:37]
	v_add_f32_e32 v23, v29, v23
	v_lshlrev_b32_e32 v8, 16, v9
	v_and_b32_e32 v9, 0xffff0000, v9
	v_add_f32_e32 v23, v38, v23
	v_pk_mul_f32 v[40:41], v[8:9], v[8:9]
	v_add_f32_e32 v23, v39, v23
	v_and_b32_e32 v43, 0xffff0000, v2
	v_add_f32_e32 v23, v40, v23
	v_pk_mul_f32 v[44:45], v[42:43], v[42:43]
	v_add_f32_e32 v23, v41, v23
	v_lshlrev_b32_e32 v2, 16, v3
	v_and_b32_e32 v3, 0xffff0000, v3
	v_add_f32_e32 v23, v44, v23
	v_pk_mul_f32 v[46:47], v[2:3], v[2:3]
	v_add_f32_e32 v23, v45, v23
	v_and_b32_e32 v10, 0xffff0000, v4
	v_lshlrev_b32_e32 v11, 16, v4
	v_add_f32_e32 v23, v46, v23
	v_pk_mul_f32 v[12:13], v[10:11], v[10:11]
	v_add_f32_e32 v23, v47, v23
	v_and_b32_e32 v4, 0xffff0000, v5
	v_lshlrev_b32_e32 v5, 16, v5
	v_add_f32_e32 v13, v13, v23
	v_pk_mul_f32 v[14:15], v[4:5], v[4:5]
	v_add_f32_e32 v12, v12, v13
	v_add_f32_e32 v12, v15, v12
	v_add_f32_e32 v12, v14, v12
	ds_bpermute_b32 v13, v31, v12
	v_add_u32_e32 v28, s10, v18
	v_mad_i64_i32 v[26:27], s[10:11], v28, s19, v[26:27]
	v_lshl_add_u64 v[26:27], v[26:27], 0, s[30:31]
	s_waitcnt lgkmcnt(0)
	v_add_f32_e32 v12, v12, v13
	ds_bpermute_b32 v13, v32, v12
	v_mov_b32_e32 v23, v1
	v_lshl_add_u64 v[26:27], v[26:27], 0, v[22:23]
	v_ashrrev_i32_e32 v29, 31, v28
	v_lshlrev_b64 v[28:29], 11, v[28:29]
	s_waitcnt lgkmcnt(0)
	v_add_f32_e32 v12, v12, v13
	v_fmamk_f32 v12, v12, 0x3c800000, v175
	v_cmp_gt_f32_e32 vcc, s15, v12
	v_mul_f32_e32 v13, 0x4b800000, v12
	v_lshl_add_u64 v[28:29], s[8:9], 0, v[28:29]
	v_cndmask_b32_e32 v12, v12, v13, vcc
	v_rsq_f32_e32 v12, v12
	v_lshl_add_u64 v[28:29], v[28:29], 0, s[30:31]
	v_mul_f32_e32 v13, 0x45800000, v12
	v_cndmask_b32_e32 v12, v12, v13, vcc
	v_pk_mul_f32 v[14:15], v[12:13], v[16:17] op_sel_hi:[0,1]
	v_cvt_pk_bf16_f32 v13, v14, v15
	v_pk_mul_f32 v[6:7], v[12:13], v[6:7] op_sel_hi:[0,1]
	v_cvt_pk_bf16_f32 v6, v6, v7
	ds_write_b16 v34, v13 offset:8192
	ds_write_b16_d16_hi v34, v13 offset:8464
	ds_write_b16 v34, v6 offset:8736
	ds_write_b16_d16_hi v34, v6 offset:9008
	v_pk_mul_f32 v[6:7], v[12:13], v[36:37] op_sel_hi:[0,1]
	v_cvt_pk_bf16_f32 v6, v6, v7
	ds_write_b16 v34, v6 offset:9280
	ds_write_b16_d16_hi v34, v6 offset:9552
	v_pk_mul_f32 v[6:7], v[12:13], v[8:9] op_sel_hi:[0,1]
	v_cvt_pk_bf16_f32 v6, v6, v7
	ds_write_b16 v34, v6 offset:9824
	ds_write_b16_d16_hi v34, v6 offset:10096
	v_pk_mul_f32 v[6:7], v[12:13], v[42:43] op_sel_hi:[0,1]
	v_pk_mul_f32 v[2:3], v[12:13], v[2:3] op_sel_hi:[0,1]
	v_cvt_pk_bf16_f32 v6, v6, v7
	v_cvt_pk_bf16_f32 v2, v2, v3
	ds_write_b16 v34, v6 offset:10368
	ds_write_b16_d16_hi v34, v6 offset:10640
	ds_write_b16 v34, v2 offset:10912
	ds_write_b16_d16_hi v34, v2 offset:11184
	v_pk_mul_f32 v[2:3], v[12:13], v[10:11] op_sel_hi:[0,1]
	v_pk_mov_b32 v[2:3], v[2:3], v[2:3] op_sel:[1,0]
	s_nop 0
	v_cvt_pk_bf16_f32 v2, v2, v3
	ds_write_b16 v34, v2 offset:11456
	ds_write_b16_d16_hi v34, v2 offset:11728
	v_pk_mul_f32 v[2:3], v[12:13], v[4:5] op_sel_hi:[0,1]
	v_pk_mov_b32 v[2:3], v[2:3], v[2:3] op_sel:[1,0]
	s_nop 0
	v_cvt_pk_bf16_f32 v2, v2, v3
	ds_write_b16 v34, v2 offset:12000
	ds_write_b16_d16_hi v34, v2 offset:12272
	v_lshl_add_u64 v[2:3], v[18:19], 0, s[30:31]
	v_lshlrev_b64 v[2:3], 9, v[2:3]
	v_lshl_add_u64 v[24:25], v[20:21], 0, v[2:3]
	s_waitcnt lgkmcnt(0)
	s_barrier
	s_waitcnt vmcnt(9)
	ds_read_b128 v[36:39], v33 offset:8192
	ds_read_b128 v[40:43], v33 offset:8224
	v_cvt_pk_bf16_f32 v44, v196, v197
	v_cvt_pk_bf16_f32 v45, v198, v199
	v_cvt_pk_bf16_f32 v46, v200, v201
	v_cvt_pk_bf16_f32 v47, v202, v203
	s_waitcnt lgkmcnt(1)
	s_nop 1
	v_mfma_f32_32x32x16_bf16 v[2:17], v[36:39], v[44:47], 0
	ds_read_b128 v[36:39], v33 offset:8256
	v_cvt_pk_bf16_f32 v56, v204, v205
	v_cvt_pk_bf16_f32 v57, v206, v207
	v_cvt_pk_bf16_f32 v58, v208, v209
	v_cvt_pk_bf16_f32 v59, v210, v211
	s_waitcnt lgkmcnt(1)
	s_nop 1
	v_mfma_f32_32x32x16_bf16 v[2:17], v[40:43], v[56:59], v[2:17]
	ds_read_b128 v[40:43], v33 offset:8288
	v_cvt_pk_bf16_f32 v44, v212, v213
	v_cvt_pk_bf16_f32 v45, v214, v215
	v_cvt_pk_bf16_f32 v46, v216, v217
	v_cvt_pk_bf16_f32 v47, v218, v219
	s_waitcnt lgkmcnt(1)
	s_nop 1
	v_mfma_f32_32x32x16_bf16 v[2:17], v[36:39], v[44:47], v[2:17]
	ds_read_b128 v[36:39], v33 offset:8320
	v_cvt_pk_bf16_f32 v56, v220, v221
	v_cvt_pk_bf16_f32 v57, v222, v223
	v_cvt_pk_bf16_f32 v58, v224, v225
	v_cvt_pk_bf16_f32 v59, v226, v227
	s_waitcnt lgkmcnt(1)
	s_nop 1
	v_mfma_f32_32x32x16_bf16 v[2:17], v[40:43], v[56:59], v[2:17]
	ds_read_b128 v[40:43], v33 offset:8352
	v_cvt_pk_bf16_f32 v44, v228, v229
	v_cvt_pk_bf16_f32 v45, v230, v231
	v_cvt_pk_bf16_f32 v46, v232, v233
	v_cvt_pk_bf16_f32 v47, v234, v235
	s_waitcnt lgkmcnt(1)
	s_nop 1
	v_mfma_f32_32x32x16_bf16 v[2:17], v[36:39], v[44:47], v[2:17]
	ds_read_b128 v[36:39], v33 offset:8384
	v_cvt_pk_bf16_f32 v56, v236, v237
	v_cvt_pk_bf16_f32 v57, v238, v239
	v_cvt_pk_bf16_f32 v58, v240, v241
	v_cvt_pk_bf16_f32 v59, v242, v243
	s_waitcnt lgkmcnt(1)
	s_nop 1
	v_mfma_f32_32x32x16_bf16 v[2:17], v[40:43], v[56:59], v[2:17]
	ds_read_b128 v[40:43], v33 offset:8416
	v_cvt_pk_bf16_f32 v44, v244, v245
	v_cvt_pk_bf16_f32 v45, v246, v247
	v_cvt_pk_bf16_f32 v46, v248, v249
	v_cvt_pk_bf16_f32 v47, v250, v251
	s_waitcnt lgkmcnt(1)
	s_nop 1
	v_mfma_f32_32x32x16_bf16 v[2:17], v[36:39], v[44:47], v[2:17]
	v_cvt_pk_bf16_f32 v56, v48, v49
	v_cvt_pk_bf16_f32 v57, v50, v51
	v_cvt_pk_bf16_f32 v58, v52, v53
	v_cvt_pk_bf16_f32 v59, v54, v55
	s_waitcnt lgkmcnt(0)
	s_nop 1
	v_mfma_f32_32x32x16_bf16 v[2:17], v[40:43], v[56:59], v[2:17]
	s_waitcnt vmcnt(0)
	s_nop 7
	s_nop 3
	v_mov_b32_e32 v24, v68
	v_mov_b32_e32 v36, v60
	v_mov_b32_e32 v37, v61
	v_mov_b32_e32 v38, v166
	v_mov_b32_e32 v39, v167
	v_lshlrev_b32_e32 v42, 16, v36
	v_lshlrev_b32_e32 v25, 16, v38
	v_and_b32_e32 v35, 0xffff0000, v38
	v_mul_f32_e32 v38, 0xbfb8aa3b, v25
	v_and_b32_e32 v43, 0xffff0000, v36
	v_mul_f32_e32 v36, 0xbfb8aa3b, v35
	v_exp_f32_e32 v40, v38
	v_exp_f32_e32 v41, v36
	v_pk_add_f32 v[2:3], v[24:25], v[2:3] op_sel_hi:[0,1]
	v_pk_mul_f32 v[2:3], v[2:3], v[42:43]
	v_pk_add_f32 v[40:41], v[40:41], 1.0 op_sel_hi:[1,0]
	s_nop 0
	v_div_scale_f32 v36, s[10:11], v41, v41, v35
	v_rcp_f32_e32 v38, v36
	s_nop 0
	v_fma_f32 v42, -v36, v38, 1.0
	v_fmac_f32_e32 v38, v42, v38
	v_div_scale_f32 v42, vcc, v35, v41, v35
	v_mul_f32_e32 v43, v42, v38
	v_fma_f32 v44, -v36, v43, v42
	v_fmac_f32_e32 v43, v44, v38
	v_fma_f32 v36, -v36, v43, v42
	v_div_fmas_f32 v36, v36, v38, v43
	v_div_fixup_f32 v41, v36, v41, v35
	v_div_scale_f32 v35, s[10:11], v40, v40, v25
	v_rcp_f32_e32 v36, v35
	s_nop 0
	v_fma_f32 v38, -v35, v36, 1.0
	v_fmac_f32_e32 v36, v38, v36
	v_div_scale_f32 v38, vcc, v25, v40, v25
	v_mul_f32_e32 v42, v38, v36
	v_fma_f32 v43, -v35, v42, v38
	v_fmac_f32_e32 v42, v43, v36
	v_fma_f32 v35, -v35, v42, v38
	v_div_fmas_f32 v35, v35, v36, v42
	v_div_fixup_f32 v40, v35, v40, v25
	v_lshlrev_b32_e32 v25, 16, v39
	v_and_b32_e32 v35, 0xffff0000, v39
	v_mul_f32_e32 v36, 0xbfb8aa3b, v25
	v_lshlrev_b32_e32 v38, 16, v37
	v_and_b32_e32 v39, 0xffff0000, v37
	v_mul_f32_e32 v37, 0xbfb8aa3b, v35
	v_exp_f32_e32 v36, v36
	v_exp_f32_e32 v37, v37
	v_pk_add_f32 v[4:5], v[24:25], v[4:5] op_sel_hi:[0,1]
	v_pk_mul_f32 v[4:5], v[4:5], v[38:39]
	v_pk_mul_f32 v[2:3], v[2:3], v[40:41]
	v_pk_add_f32 v[36:37], v[36:37], 1.0 op_sel_hi:[1,0]
	s_nop 0
	v_div_scale_f32 v38, s[10:11], v37, v37, v35
	v_rcp_f32_e32 v39, v38
	s_nop 0
	v_fma_f32 v40, -v38, v39, 1.0
	v_fmac_f32_e32 v39, v40, v39
	v_div_scale_f32 v40, vcc, v35, v37, v35
	v_mul_f32_e32 v41, v40, v39
	v_fma_f32 v42, -v38, v41, v40
	v_fmac_f32_e32 v41, v42, v39
	v_fma_f32 v38, -v38, v41, v40
	v_div_fmas_f32 v38, v38, v39, v41
	v_div_fixup_f32 v37, v38, v37, v35
	v_div_scale_f32 v35, s[10:11], v36, v36, v25
	v_rcp_f32_e32 v38, v35
	s_nop 0
	v_fma_f32 v39, -v35, v38, 1.0
	v_fmac_f32_e32 v38, v39, v38
	v_div_scale_f32 v39, vcc, v25, v36, v25
	v_mul_f32_e32 v40, v39, v38
	v_fma_f32 v41, -v35, v40, v39
	v_fmac_f32_e32 v40, v41, v38
	v_fma_f32 v35, -v35, v40, v39
	v_div_fmas_f32 v35, v35, v38, v40
	v_div_fixup_f32 v36, v35, v36, v25
	v_pk_mul_f32 v[4:5], v[4:5], v[36:37]
	v_cvt_pk_bf16_f32 v36, v2, v3
	v_cvt_pk_bf16_f32 v37, v4, v5
	v_lshl_add_u64 v[2:3], v[28:29], 0, v[22:23]
	global_store_dwordx2 v[2:3], v[36:37], off
	v_mov_b32_e32 v4, v62
	v_mov_b32_e32 v5, v63
	v_mov_b32_e32 v28, v168
	v_mov_b32_e32 v29, v169
	v_lshlrev_b32_e32 v38, 16, v4
	v_lshlrev_b32_e32 v23, 16, v28
	v_and_b32_e32 v25, 0xffff0000, v28
	v_mul_f32_e32 v28, 0xbfb8aa3b, v23
	v_and_b32_e32 v39, 0xffff0000, v4
	v_mul_f32_e32 v4, 0xbfb8aa3b, v25
	v_exp_f32_e32 v36, v28
	v_exp_f32_e32 v37, v4
	v_pk_add_f32 v[6:7], v[24:25], v[6:7] op_sel_hi:[0,1]
	v_pk_mul_f32 v[6:7], v[6:7], v[38:39]
	v_pk_add_f32 v[36:37], v[36:37], 1.0 op_sel_hi:[1,0]
	s_nop 0
	v_div_scale_f32 v4, s[10:11], v37, v37, v25
	v_rcp_f32_e32 v28, v4
	s_nop 0
	v_fma_f32 v35, -v4, v28, 1.0
	v_fmac_f32_e32 v28, v35, v28
	v_div_scale_f32 v35, vcc, v25, v37, v25
	v_mul_f32_e32 v38, v35, v28
	v_fma_f32 v39, -v4, v38, v35
	v_fmac_f32_e32 v38, v39, v28
	v_fma_f32 v4, -v4, v38, v35
	v_div_fmas_f32 v4, v4, v28, v38
	v_div_fixup_f32 v37, v4, v37, v25
	v_div_scale_f32 v4, s[10:11], v36, v36, v23
	v_rcp_f32_e32 v25, v4
	s_nop 0
	v_fma_f32 v28, -v4, v25, 1.0
	v_fmac_f32_e32 v25, v28, v25
	v_div_scale_f32 v28, vcc, v23, v36, v23
	v_mul_f32_e32 v35, v28, v25
	v_fma_f32 v38, -v4, v35, v28
	v_fmac_f32_e32 v35, v38, v25
	v_fma_f32 v4, -v4, v35, v28
	v_div_fmas_f32 v4, v4, v25, v35
	v_div_fixup_f32 v36, v4, v36, v23
	v_lshlrev_b32_e32 v23, 16, v29
	v_and_b32_e32 v25, 0xffff0000, v29
	v_mul_f32_e32 v4, 0xbfb8aa3b, v23
	v_lshlrev_b32_e32 v28, 16, v5
	v_and_b32_e32 v29, 0xffff0000, v5
	v_mul_f32_e32 v5, 0xbfb8aa3b, v25
	v_exp_f32_e32 v4, v4
	v_exp_f32_e32 v5, v5
	v_pk_add_f32 v[8:9], v[24:25], v[8:9] op_sel_hi:[0,1]
	v_pk_mul_f32 v[8:9], v[8:9], v[28:29]
	v_pk_mul_f32 v[6:7], v[6:7], v[36:37]
	v_pk_add_f32 v[4:5], v[4:5], 1.0 op_sel_hi:[1,0]
	v_cvt_pk_bf16_f32 v6, v6, v7
	v_div_scale_f32 v28, s[10:11], v5, v5, v25
	v_rcp_f32_e32 v29, v28
	s_nop 0
	v_fma_f32 v35, -v28, v29, 1.0
	v_fmac_f32_e32 v29, v35, v29
	v_div_scale_f32 v35, vcc, v25, v5, v25
	v_mul_f32_e32 v36, v35, v29
	v_fma_f32 v37, -v28, v36, v35
	v_fmac_f32_e32 v36, v37, v29
	v_fma_f32 v28, -v28, v36, v35
	v_div_fmas_f32 v28, v28, v29, v36
	v_div_fixup_f32 v5, v28, v5, v25
	v_div_scale_f32 v25, s[10:11], v4, v4, v23
	v_rcp_f32_e32 v28, v25
	s_nop 0
	v_fma_f32 v29, -v25, v28, 1.0
	v_fmac_f32_e32 v28, v29, v28
	v_div_scale_f32 v29, vcc, v23, v4, v23
	v_mul_f32_e32 v35, v29, v28
	v_fma_f32 v36, -v25, v35, v29
	v_fmac_f32_e32 v35, v36, v28
	v_fma_f32 v25, -v25, v35, v29
	v_div_fmas_f32 v25, v25, v28, v35
	v_div_fixup_f32 v4, v25, v4, v23
	v_pk_mul_f32 v[4:5], v[8:9], v[4:5]
	v_pk_add_f32 v[10:11], v[24:25], v[10:11] op_sel_hi:[0,1]
	v_cvt_pk_bf16_f32 v7, v4, v5
	global_store_dwordx2 v[2:3], v[6:7], off offset:16
	v_mov_b32_e32 v4, v64
	v_mov_b32_e32 v5, v65
	v_mov_b32_e32 v6, v170
	v_mov_b32_e32 v7, v171
	v_lshlrev_b32_e32 v28, 16, v4
	v_lshlrev_b32_e32 v23, 16, v6
	v_and_b32_e32 v6, 0xffff0000, v6
	v_mul_f32_e32 v8, 0xbfb8aa3b, v23
	v_and_b32_e32 v29, 0xffff0000, v4
	v_mul_f32_e32 v4, 0xbfb8aa3b, v6
	v_exp_f32_e32 v8, v8
	v_exp_f32_e32 v9, v4
	v_pk_mul_f32 v[10:11], v[10:11], v[28:29]
	v_pk_add_f32 v[8:9], v[8:9], 1.0 op_sel_hi:[1,0]
	s_nop 0
	v_div_scale_f32 v4, s[10:11], v9, v9, v6
	v_rcp_f32_e32 v25, v4
	s_nop 0
	v_fma_f32 v28, -v4, v25, 1.0
	v_fmac_f32_e32 v25, v28, v25
	v_div_scale_f32 v28, vcc, v6, v9, v6
	v_mul_f32_e32 v29, v28, v25
	v_fma_f32 v35, -v4, v29, v28
	v_fmac_f32_e32 v29, v35, v25
	v_fma_f32 v4, -v4, v29, v28
	v_div_fmas_f32 v4, v4, v25, v29
	v_div_fixup_f32 v9, v4, v9, v6
	v_div_scale_f32 v4, s[10:11], v8, v8, v23
	v_rcp_f32_e32 v6, v4
	s_nop 0
	v_fma_f32 v25, -v4, v6, 1.0
	v_fmac_f32_e32 v6, v25, v6
	v_div_scale_f32 v25, vcc, v23, v8, v23
	v_mul_f32_e32 v28, v25, v6
	v_fma_f32 v29, -v4, v28, v25
	v_fmac_f32_e32 v28, v29, v6
	v_fma_f32 v4, -v4, v28, v25
	v_div_fmas_f32 v4, v4, v6, v28
	v_div_fixup_f32 v8, v4, v8, v23
	v_lshlrev_b32_e32 v23, 16, v7
	v_and_b32_e32 v25, 0xffff0000, v7
	v_mul_f32_e32 v4, 0xbfb8aa3b, v23
	v_lshlrev_b32_e32 v6, 16, v5
	v_and_b32_e32 v7, 0xffff0000, v5
	v_mul_f32_e32 v5, 0xbfb8aa3b, v25
	v_exp_f32_e32 v4, v4
	v_exp_f32_e32 v5, v5
	v_pk_mul_f32 v[8:9], v[10:11], v[8:9]
	v_pk_add_f32 v[10:11], v[24:25], v[12:13] op_sel_hi:[0,1]
	v_pk_mul_f32 v[6:7], v[10:11], v[6:7]
	v_pk_add_f32 v[4:5], v[4:5], 1.0 op_sel_hi:[1,0]
	s_nop 0
	v_div_scale_f32 v10, s[10:11], v5, v5, v25
	v_rcp_f32_e32 v11, v10
	s_nop 0
	v_fma_f32 v12, -v10, v11, 1.0
	v_fmac_f32_e32 v11, v12, v11
	v_div_scale_f32 v12, vcc, v25, v5, v25
	v_mul_f32_e32 v13, v12, v11
	v_fma_f32 v28, -v10, v13, v12
	v_fmac_f32_e32 v13, v28, v11
	v_fma_f32 v10, -v10, v13, v12
	v_div_fmas_f32 v10, v10, v11, v13
	v_div_fixup_f32 v5, v10, v5, v25
	v_div_scale_f32 v10, s[10:11], v4, v4, v23
	v_rcp_f32_e32 v11, v10
	s_nop 0
	v_fma_f32 v12, -v10, v11, 1.0
	v_fmac_f32_e32 v11, v12, v11
	v_div_scale_f32 v12, vcc, v23, v4, v23
	v_mul_f32_e32 v13, v12, v11
	v_fma_f32 v25, -v10, v13, v12
	v_fmac_f32_e32 v13, v25, v11
	v_fma_f32 v10, -v10, v13, v12
	v_div_fmas_f32 v10, v10, v11, v13
	v_div_fixup_f32 v4, v10, v4, v23
	v_pk_mul_f32 v[4:5], v[6:7], v[4:5]
	v_cvt_pk_bf16_f32 v6, v8, v9
	v_cvt_pk_bf16_f32 v7, v4, v5
	global_store_dwordx2 v[2:3], v[6:7], off offset:32
	v_mov_b32_e32 v4, v66
	v_mov_b32_e32 v5, v67
	v_mov_b32_e32 v6, v172
	v_mov_b32_e32 v7, v173
	v_pk_add_f32 v[12:13], v[24:25], v[14:15] op_sel_hi:[0,1]
	v_lshlrev_b32_e32 v10, 16, v4
	v_lshlrev_b32_e32 v23, 16, v6
	v_and_b32_e32 v6, 0xffff0000, v6
	v_mul_f32_e32 v8, 0xbfb8aa3b, v23
	v_and_b32_e32 v11, 0xffff0000, v4
	v_mul_f32_e32 v4, 0xbfb8aa3b, v6
	v_exp_f32_e32 v8, v8
	v_exp_f32_e32 v9, v4
	v_pk_mul_f32 v[10:11], v[12:13], v[10:11]
	v_pk_add_f32 v[8:9], v[8:9], 1.0 op_sel_hi:[1,0]
	s_nop 0
	v_div_scale_f32 v4, s[10:11], v9, v9, v6
	v_rcp_f32_e32 v12, v4
	s_nop 0
	v_fma_f32 v13, -v4, v12, 1.0
	v_fmac_f32_e32 v12, v13, v12
	v_div_scale_f32 v13, vcc, v6, v9, v6
	v_mul_f32_e32 v14, v13, v12
	v_fma_f32 v15, -v4, v14, v13
	v_fmac_f32_e32 v14, v15, v12
	v_fma_f32 v4, -v4, v14, v13
	v_div_fmas_f32 v4, v4, v12, v14
	v_div_fixup_f32 v9, v4, v9, v6
	v_div_scale_f32 v4, s[10:11], v8, v8, v23
	v_rcp_f32_e32 v6, v4
	s_nop 0
	v_fma_f32 v12, -v4, v6, 1.0
	v_fmac_f32_e32 v6, v12, v6
	v_div_scale_f32 v12, vcc, v23, v8, v23
	v_mul_f32_e32 v13, v12, v6
	v_fma_f32 v14, -v4, v13, v12
	v_fmac_f32_e32 v13, v14, v6
	v_fma_f32 v4, -v4, v13, v12
	v_div_fmas_f32 v4, v4, v6, v13
	v_lshlrev_b32_e32 v12, 16, v7
	v_and_b32_e32 v13, 0xffff0000, v7
	v_div_fixup_f32 v8, v4, v8, v23
	v_mul_f32_e32 v4, 0xbfb8aa3b, v12
	v_lshlrev_b32_e32 v6, 16, v5
	v_and_b32_e32 v7, 0xffff0000, v5
	v_mul_f32_e32 v5, 0xbfb8aa3b, v13
	v_exp_f32_e32 v4, v4
	v_exp_f32_e32 v5, v5
	v_pk_mul_f32 v[8:9], v[10:11], v[8:9]
	v_pk_add_f32 v[10:11], v[24:25], v[16:17] op_sel_hi:[0,1]
	v_pk_mul_f32 v[6:7], v[10:11], v[6:7]
	v_pk_add_f32 v[4:5], v[4:5], 1.0 op_sel_hi:[1,0]
	s_nop 0
	v_div_scale_f32 v10, s[10:11], v5, v5, v13
	v_rcp_f32_e32 v11, v10
	s_nop 0
	v_fma_f32 v14, -v10, v11, 1.0
	v_fmac_f32_e32 v11, v14, v11
	v_div_scale_f32 v14, vcc, v13, v5, v13
	v_mul_f32_e32 v15, v14, v11
	v_fma_f32 v16, -v10, v15, v14
	v_fmac_f32_e32 v15, v16, v11
	v_fma_f32 v10, -v10, v15, v14
	v_div_fmas_f32 v10, v10, v11, v15
	v_div_fixup_f32 v5, v10, v5, v13
	v_div_scale_f32 v10, s[10:11], v4, v4, v12
	v_rcp_f32_e32 v11, v10
	s_nop 0
	v_fma_f32 v13, -v10, v11, 1.0
	v_fmac_f32_e32 v11, v13, v11
	v_div_scale_f32 v13, vcc, v12, v4, v12
	v_mul_f32_e32 v14, v13, v11
	v_fma_f32 v15, -v10, v14, v13
	v_fmac_f32_e32 v14, v15, v11
	v_fma_f32 v10, -v10, v14, v13
	v_div_fmas_f32 v10, v10, v11, v14
	v_div_fixup_f32 v4, v10, v4, v12
	v_pk_mul_f32 v[4:5], v[6:7], v[4:5]
	v_cvt_pk_bf16_f32 v6, v8, v9
	v_cvt_pk_bf16_f32 v7, v4, v5
	global_store_dwordx2 v[2:3], v[6:7], off offset:48
	s_barrier
	s_cbranch_scc1 .LBB0_169

.LBB0_169:
	s_cmpk_lt_i32 s58, 0x80
	v_readlane_b32 s80, v255, 0
	v_lshl_add_u32 v58, s58, 9, v100
	s_cselect_b64 s[0:1], -1, 0
	s_mov_b32 s2, 0x60000
	v_readlane_b32 s94, v255, 14
	v_readlane_b32 s95, v255, 15
	s_or_b64 s[0:1], s[42:43], s[0:1]
	v_cmp_gt_i32_e32 vcc, s2, v58
	s_mov_b64 s[10:11], s[94:95]
	s_and_b64 s[0:1], s[0:1], vcc
	v_readlane_b32 s81, v255, 1
	v_readlane_b32 s82, v255, 2
	v_readlane_b32 s83, v255, 3
	v_readlane_b32 s84, v255, 4
	v_readlane_b32 s85, v255, 5
	v_readlane_b32 s86, v255, 6
	v_readlane_b32 s87, v255, 7
	v_readlane_b32 s88, v255, 8
	v_readlane_b32 s89, v255, 9
	v_readlane_b32 s90, v255, 10
	v_readlane_b32 s91, v255, 11
	v_readlane_b32 s92, v255, 12
	v_readlane_b32 s93, v255, 13
	s_and_saveexec_b64 s[4:5], s[0:1]
	s_movk_i32 s20, 0x3ff
	v_readlane_b32 s30, v255, 61
	v_readlane_b32 s17, v255, 59
	v_readlane_b32 s21, v255, 60
	s_cbranch_execz .LBB0_176
	s_mul_i32 s30, s34, 0x300
	s_lshl_b64 s[0:1], s[30:31], 2
	s_add_u32 s10, s10, s0
	v_lshlrev_b32_e32 v0, 3, v100
	v_readlane_b32 s30, v255, 61
	v_readlane_b32 s21, v255, 60
	v_readlane_b32 s17, v255, 59
	s_addc_u32 s11, s11, s1
	v_and_b32_e32 v59, 31, v100
	v_lshrrev_b32_e32 v58, 5, v100
	v_lshlrev_b32_e32 v60, 5, v59
	v_lshlrev_b32_e32 v59, 4, v59
	s_cmpk_lt_i32 s58, 0x80
	s_cselect_b32 s74, 6, 0
	s_cselect_b32 s1, 0, 0x2800
	s_lshl_b32 s0, s58, 4
	s_add_u32 s0, s0, s1
	v_add_u32_e32 v58, s0, v58
	s_cmp_eq_u32 s74, 0
	s_cbranch_scc1 .Lcv_done
	global_load_dwordx4 v[196:199], v60, s[10:11]
	global_load_dwordx4 v[200:203], v60, s[10:11] offset:16
	global_load_dwordx4 v[204:207], v60, s[10:11] offset:1024
	global_load_dwordx4 v[208:211], v60, s[10:11] offset:1040
	global_load_dwordx4 v[212:215], v60, s[10:11] offset:2048
	global_load_dwordx4 v[216:219], v60, s[10:11] offset:2064
	s_mov_b32 s22, 0xffff0000
	s_mov_b32 s23, 0xbfb8aa3b
	v_mov_b32_e32 v66, 0xff
	v_mov_b32_e32 v67, 0xfff
	v_mov_b32_e32 v68, 0x1c00
	v_cmp_lt_u32_e32 vcc, 0xfff, v58
	v_mad_u32_u24 v54, v58, v68, v59
	s_nop 0
	v_cndmask_b32_e32 v52, v66, v67, vcc
	v_and_b32_e32 v53, v52, v58
	v_cmp_ne_u32_e32 vcc, 0, v53
	s_nop 1
	v_cndmask_b32_e32 v55, 0, v68, vcc
	v_cmp_ne_u32_e32 vcc, v53, v52
	v_sub_u32_e32 v55, v54, v55
	s_nop 0
	v_cndmask_b32_e32 v56, 0, v68, vcc
	v_add_u32_e32 v56, v54, v56
	global_load_dwordx4 v[220:223], v54, s[6:7] offset:1536
	global_load_dwordx4 v[224:227], v54, s[6:7] offset:2048
	global_load_dwordx4 v[228:231], v54, s[6:7] offset:2560
	global_load_dwordx4 v[232:235], v54, s[6:7] offset:3072
	global_load_dwordx4 v[236:239], v55, s[6:7] offset:2048
	global_load_dwordx4 v[240:243], v55, s[6:7] offset:2560
	global_load_dwordx4 v[244:247], v56, s[6:7] offset:2048
	global_load_dwordx4 v[248:251], v56, s[6:7] offset:2560
.Lcv_loop:
	s_cmp_lt_u32 s74, 2
	s_cbranch_scc1 .Lcv_a_last
	v_add_u32_e32 v60, 0x800, v58
	v_cmp_lt_u32_e32 vcc, 0xfff, v60
	v_mad_u32_u24 v54, v60, v68, v59
	s_nop 0
	v_cndmask_b32_e32 v52, v66, v67, vcc
	v_and_b32_e32 v53, v52, v60
	v_cmp_ne_u32_e32 vcc, 0, v53
	s_nop 1
	v_cndmask_b32_e32 v55, 0, v68, vcc
	v_cmp_ne_u32_e32 vcc, v53, v52
	v_sub_u32_e32 v55, v54, v55
	s_nop 0
	v_cndmask_b32_e32 v56, 0, v68, vcc
	v_add_u32_e32 v56, v54, v56
	global_load_dwordx4 v[2:5], v54, s[6:7] offset:1536
	global_load_dwordx4 v[6:9], v54, s[6:7] offset:2048
	global_load_dwordx4 v[10:13], v54, s[6:7] offset:2560
	global_load_dwordx4 v[14:17], v54, s[6:7] offset:3072
	global_load_dwordx4 v[18:21], v55, s[6:7] offset:2048
	global_load_dwordx4 v[22:25], v55, s[6:7] offset:2560
	global_load_dwordx4 v[26:29], v56, s[6:7] offset:2048
	global_load_dwordx4 v[30:33], v56, s[6:7] offset:2560
	s_waitcnt vmcnt(8)
	s_branch .Lcv_a_go

.Lcv_a_go:
	v_cmp_lt_u32_e32 vcc, 0xfff, v58
	v_lshl_add_u32 v61, v58, 11, v59
	s_nop 0
	v_cndmask_b32_e32 v52, v66, v67, vcc
	v_and_b32_e32 v53, v52, v58
	v_cmp_ne_u32_e64 s[0:1], 0, v53
	v_cmp_ne_u32_e32 vcc, v53, v52
	s_nop 1
	v_cndmask_b32_e64 v240, 0, v240, s[0:1]
	v_cndmask_b32_e64 v241, 0, v241, s[0:1]
	v_cndmask_b32_e64 v242, 0, v242, s[0:1]
	v_cndmask_b32_e64 v243, 0, v243, s[0:1]
	v_cndmask_b32_e32 v248, 0, v248, vcc
	v_cndmask_b32_e32 v249, 0, v249, vcc
	v_cndmask_b32_e32 v250, 0, v250, vcc
	v_cndmask_b32_e32 v251, 0, v251, vcc
	v_lshlrev_b32_e32 v48, 16, v232
	v_and_b32_e32 v49, s22, v232
	v_mul_f32_e32 v50, s23, v48
	v_mul_f32_e32 v51, s23, v49
	v_exp_f32_e32 v50, v50
	v_exp_f32_e32 v51, v51
	v_lshlrev_b32_e32 v34, 16, v236
	v_and_b32_e32 v35, s22, v236
	v_lshlrev_b32_e32 v36, 16, v240
	v_and_b32_e32 v37, s22, v240
	v_lshlrev_b32_e32 v38, 16, v224
	v_and_b32_e32 v39, s22, v224
	v_lshlrev_b32_e32 v40, 16, v228
	v_and_b32_e32 v41, s22, v228
	v_lshlrev_b32_e32 v42, 16, v244
	v_and_b32_e32 v43, s22, v244
	v_lshlrev_b32_e32 v44, 16, v248
	v_and_b32_e32 v45, s22, v248
	v_lshlrev_b32_e32 v46, 16, v220
	v_and_b32_e32 v47, s22, v220
	v_pk_mul_f32 v[34:35], v[34:35], v[36:37]
	v_pk_mul_f32 v[38:39], v[38:39], v[40:41]
	v_pk_mul_f32 v[42:43], v[42:43], v[44:45]
	v_pk_mul_f32 v[34:35], v[34:35], v[196:197]
	v_pk_add_f32 v[50:51], v[50:51], 1.0 op_sel_hi:[1,0]
	v_pk_fma_f32 v[34:35], v[38:39], v[204:205], v[34:35]
	s_nop 0
	v_pk_fma_f32 v[34:35], v[42:43], v[212:213], v[34:35]
	s_nop 0
	v_pk_mul_f32 v[34:35], v[34:35], v[46:47]
	v_div_scale_f32 v52, s[0:1], v51, v51, v49
	v_rcp_f32_e32 v53, v52
	s_nop 0
	v_fma_f32 v54, -v52, v53, 1.0
	v_fmac_f32_e32 v53, v54, v53
	v_div_scale_f32 v54, vcc, v49, v51, v49
	v_mul_f32_e32 v55, v54, v53
	v_fma_f32 v56, -v52, v55, v54
	v_fmac_f32_e32 v55, v56, v53
	v_fma_f32 v52, -v52, v55, v54
	v_div_fmas_f32 v52, v52, v53, v55
	v_div_fixup_f32 v51, v52, v51, v49
	v_div_scale_f32 v52, s[0:1], v50, v50, v48
	v_rcp_f32_e32 v53, v52
	s_nop 0
	v_fma_f32 v54, -v52, v53, 1.0
	v_fmac_f32_e32 v53, v54, v53
	v_div_scale_f32 v54, vcc, v48, v50, v48
	v_mul_f32_e32 v55, v54, v53
	v_fma_f32 v56, -v52, v55, v54
	v_fmac_f32_e32 v55, v56, v53
	v_fma_f32 v52, -v52, v55, v54
	v_div_fmas_f32 v52, v52, v53, v55
	v_div_fixup_f32 v50, v52, v50, v48
	s_nop 0
	v_pk_mul_f32 v[34:35], v[50:51], v[34:35]
	s_nop 0
	v_cvt_pk_bf16_f32 v62, v34, v35
	v_lshlrev_b32_e32 v48, 16, v233
	v_and_b32_e32 v49, s22, v233
	v_mul_f32_e32 v50, s23, v48
	v_mul_f32_e32 v51, s23, v49
	v_exp_f32_e32 v50, v50
	v_exp_f32_e32 v51, v51
	v_lshlrev_b32_e32 v34, 16, v237
	v_and_b32_e32 v35, s22, v237
	v_lshlrev_b32_e32 v36, 16, v241
	v_and_b32_e32 v37, s22, v241
	v_lshlrev_b32_e32 v38, 16, v225
	v_and_b32_e32 v39, s22, v225
	v_lshlrev_b32_e32 v40, 16, v229
	v_and_b32_e32 v41, s22, v229
	v_lshlrev_b32_e32 v42, 16, v245
	v_and_b32_e32 v43, s22, v245
	v_lshlrev_b32_e32 v44, 16, v249
	v_and_b32_e32 v45, s22, v249
	v_lshlrev_b32_e32 v46, 16, v221
	v_and_b32_e32 v47, s22, v221
	v_pk_mul_f32 v[34:35], v[34:35], v[36:37]
	v_pk_mul_f32 v[38:39], v[38:39], v[40:41]
	v_pk_mul_f32 v[42:43], v[42:43], v[44:45]
	v_pk_mul_f32 v[34:35], v[34:35], v[198:199]
	v_pk_add_f32 v[50:51], v[50:51], 1.0 op_sel_hi:[1,0]
	v_pk_fma_f32 v[34:35], v[38:39], v[206:207], v[34:35]
	s_nop 0
	v_pk_fma_f32 v[34:35], v[42:43], v[214:215], v[34:35]
	s_nop 0
	v_pk_mul_f32 v[34:35], v[34:35], v[46:47]
	v_div_scale_f32 v52, s[0:1], v51, v51, v49
	v_rcp_f32_e32 v53, v52
	s_nop 0
	v_fma_f32 v54, -v52, v53, 1.0
	v_fmac_f32_e32 v53, v54, v53
	v_div_scale_f32 v54, vcc, v49, v51, v49
	v_mul_f32_e32 v55, v54, v53
	v_fma_f32 v56, -v52, v55, v54
	v_fmac_f32_e32 v55, v56, v53
	v_fma_f32 v52, -v52, v55, v54
	v_div_fmas_f32 v52, v52, v53, v55
	v_div_fixup_f32 v51, v52, v51, v49
	v_div_scale_f32 v52, s[0:1], v50, v50, v48
	v_rcp_f32_e32 v53, v52
	s_nop 0
	v_fma_f32 v54, -v52, v53, 1.0
	v_fmac_f32_e32 v53, v54, v53
	v_div_scale_f32 v54, vcc, v48, v50, v48
	v_mul_f32_e32 v55, v54, v53
	v_fma_f32 v56, -v52, v55, v54
	v_fmac_f32_e32 v55, v56, v53
	v_fma_f32 v52, -v52, v55, v54
	v_div_fmas_f32 v52, v52, v53, v55
	v_div_fixup_f32 v50, v52, v50, v48
	s_nop 0
	v_pk_mul_f32 v[34:35], v[50:51], v[34:35]
	s_nop 0
	v_cvt_pk_bf16_f32 v63, v34, v35
	v_lshlrev_b32_e32 v48, 16, v234
	v_and_b32_e32 v49, s22, v234
	v_mul_f32_e32 v50, s23, v48
	v_mul_f32_e32 v51, s23, v49
	v_exp_f32_e32 v50, v50
	v_exp_f32_e32 v51, v51
	v_lshlrev_b32_e32 v34, 16, v238
	v_and_b32_e32 v35, s22, v238
	v_lshlrev_b32_e32 v36, 16, v242
	v_and_b32_e32 v37, s22, v242
	v_lshlrev_b32_e32 v38, 16, v226
	v_and_b32_e32 v39, s22, v226
	v_lshlrev_b32_e32 v40, 16, v230
	v_and_b32_e32 v41, s22, v230
	v_lshlrev_b32_e32 v42, 16, v246
	v_and_b32_e32 v43, s22, v246
	v_lshlrev_b32_e32 v44, 16, v250
	v_and_b32_e32 v45, s22, v250
	v_lshlrev_b32_e32 v46, 16, v222
	v_and_b32_e32 v47, s22, v222
	v_pk_mul_f32 v[34:35], v[34:35], v[36:37]
	v_pk_mul_f32 v[38:39], v[38:39], v[40:41]
	v_pk_mul_f32 v[42:43], v[42:43], v[44:45]
	v_pk_mul_f32 v[34:35], v[34:35], v[200:201]
	v_pk_add_f32 v[50:51], v[50:51], 1.0 op_sel_hi:[1,0]
	v_pk_fma_f32 v[34:35], v[38:39], v[208:209], v[34:35]
	s_nop 0
	v_pk_fma_f32 v[34:35], v[42:43], v[216:217], v[34:35]
	s_nop 0
	v_pk_mul_f32 v[34:35], v[34:35], v[46:47]
	v_div_scale_f32 v52, s[0:1], v51, v51, v49
	v_rcp_f32_e32 v53, v52
	s_nop 0
	v_fma_f32 v54, -v52, v53, 1.0
	v_fmac_f32_e32 v53, v54, v53
	v_div_scale_f32 v54, vcc, v49, v51, v49
	v_mul_f32_e32 v55, v54, v53
	v_fma_f32 v56, -v52, v55, v54
	v_fmac_f32_e32 v55, v56, v53
	v_fma_f32 v52, -v52, v55, v54
	v_div_fmas_f32 v52, v52, v53, v55
	v_div_fixup_f32 v51, v52, v51, v49
	v_div_scale_f32 v52, s[0:1], v50, v50, v48
	v_rcp_f32_e32 v53, v52
	s_nop 0
	v_fma_f32 v54, -v52, v53, 1.0
	v_fmac_f32_e32 v53, v54, v53
	v_div_scale_f32 v54, vcc, v48, v50, v48
	v_mul_f32_e32 v55, v54, v53
	v_fma_f32 v56, -v52, v55, v54
	v_fmac_f32_e32 v55, v56, v53
	v_fma_f32 v52, -v52, v55, v54
	v_div_fmas_f32 v52, v52, v53, v55
	v_div_fixup_f32 v50, v52, v50, v48
	s_nop 0
	v_pk_mul_f32 v[34:35], v[50:51], v[34:35]
	s_nop 0
	v_cvt_pk_bf16_f32 v64, v34, v35
	v_lshlrev_b32_e32 v48, 16, v235
	v_and_b32_e32 v49, s22, v235
	v_mul_f32_e32 v50, s23, v48
	v_mul_f32_e32 v51, s23, v49
	v_exp_f32_e32 v50, v50
	v_exp_f32_e32 v51, v51
	v_lshlrev_b32_e32 v34, 16, v239
	v_and_b32_e32 v35, s22, v239
	v_lshlrev_b32_e32 v36, 16, v243
	v_and_b32_e32 v37, s22, v243
	v_lshlrev_b32_e32 v38, 16, v227
	v_and_b32_e32 v39, s22, v227
	v_lshlrev_b32_e32 v40, 16, v231
	v_and_b32_e32 v41, s22, v231
	v_lshlrev_b32_e32 v42, 16, v247
	v_and_b32_e32 v43, s22, v247
	v_lshlrev_b32_e32 v44, 16, v251
	v_and_b32_e32 v45, s22, v251
	v_lshlrev_b32_e32 v46, 16, v223
	v_and_b32_e32 v47, s22, v223
	v_pk_mul_f32 v[34:35], v[34:35], v[36:37]
	v_pk_mul_f32 v[38:39], v[38:39], v[40:41]
	v_pk_mul_f32 v[42:43], v[42:43], v[44:45]
	v_pk_mul_f32 v[34:35], v[34:35], v[202:203]
	v_pk_add_f32 v[50:51], v[50:51], 1.0 op_sel_hi:[1,0]
	v_pk_fma_f32 v[34:35], v[38:39], v[210:211], v[34:35]
	s_nop 0
	v_pk_fma_f32 v[34:35], v[42:43], v[218:219], v[34:35]
	s_nop 0
	v_pk_mul_f32 v[34:35], v[34:35], v[46:47]
	v_div_scale_f32 v52, s[0:1], v51, v51, v49
	v_rcp_f32_e32 v53, v52
	s_nop 0
	v_fma_f32 v54, -v52, v53, 1.0
	v_fmac_f32_e32 v53, v54, v53
	v_div_scale_f32 v54, vcc, v49, v51, v49
	v_mul_f32_e32 v55, v54, v53
	v_fma_f32 v56, -v52, v55, v54
	v_fmac_f32_e32 v55, v56, v53
	v_fma_f32 v52, -v52, v55, v54
	v_div_fmas_f32 v52, v52, v53, v55
	v_div_fixup_f32 v51, v52, v51, v49
	v_div_scale_f32 v52, s[0:1], v50, v50, v48
	v_rcp_f32_e32 v53, v52
	s_nop 0
	v_fma_f32 v54, -v52, v53, 1.0
	v_fmac_f32_e32 v53, v54, v53
	v_div_scale_f32 v54, vcc, v48, v50, v48
	v_mul_f32_e32 v55, v54, v53
	v_fma_f32 v56, -v52, v55, v54
	v_fmac_f32_e32 v55, v56, v53
	v_fma_f32 v52, -v52, v55, v54
	v_div_fmas_f32 v52, v52, v53, v55
	v_div_fixup_f32 v50, v52, v50, v48
	s_nop 0
	v_pk_mul_f32 v[34:35], v[50:51], v[34:35]
	s_nop 0
	v_cvt_pk_bf16_f32 v65, v34, v35
	s_nop 0
	global_store_dwordx4 v61, v[62:65], s[8:9] offset:512
	v_add_u32_e32 v58, 0x800, v58
	s_sub_u32 s74, s74, 1
	s_cmp_eq_u32 s74, 0
	s_cbranch_scc1 .Lcv_done
	s_cmp_lt_u32 s74, 2
	s_cbranch_scc1 .Lcv_b_last
	v_add_u32_e32 v60, 0x800, v58
	v_cmp_lt_u32_e32 vcc, 0xfff, v60
	v_mad_u32_u24 v54, v60, v68, v59
	s_nop 0
	v_cndmask_b32_e32 v52, v66, v67, vcc
	v_and_b32_e32 v53, v52, v60
	v_cmp_ne_u32_e32 vcc, 0, v53
	s_nop 1
	v_cndmask_b32_e32 v55, 0, v68, vcc
	v_cmp_ne_u32_e32 vcc, v53, v52
	v_sub_u32_e32 v55, v54, v55
	s_nop 0
	v_cndmask_b32_e32 v56, 0, v68, vcc
	v_add_u32_e32 v56, v54, v56
	global_load_dwordx4 v[220:223], v54, s[6:7] offset:1536
	global_load_dwordx4 v[224:227], v54, s[6:7] offset:2048
	global_load_dwordx4 v[228:231], v54, s[6:7] offset:2560
	global_load_dwordx4 v[232:235], v54, s[6:7] offset:3072
	global_load_dwordx4 v[236:239], v55, s[6:7] offset:2048
	global_load_dwordx4 v[240:243], v55, s[6:7] offset:2560
	global_load_dwordx4 v[244:247], v56, s[6:7] offset:2048
	global_load_dwordx4 v[248:251], v56, s[6:7] offset:2560
	s_waitcnt vmcnt(8)
	s_branch .Lcv_b_go

.Lcv_b_go:
	v_cmp_lt_u32_e32 vcc, 0xfff, v58
	v_lshl_add_u32 v61, v58, 11, v59
	s_nop 0
	v_cndmask_b32_e32 v52, v66, v67, vcc
	v_and_b32_e32 v53, v52, v58
	v_cmp_ne_u32_e64 s[0:1], 0, v53
	v_cmp_ne_u32_e32 vcc, v53, v52
	s_nop 1
	v_cndmask_b32_e64 v22, 0, v22, s[0:1]
	v_cndmask_b32_e64 v23, 0, v23, s[0:1]
	v_cndmask_b32_e64 v24, 0, v24, s[0:1]
	v_cndmask_b32_e64 v25, 0, v25, s[0:1]
	v_cndmask_b32_e32 v30, 0, v30, vcc
	v_cndmask_b32_e32 v31, 0, v31, vcc
	v_cndmask_b32_e32 v32, 0, v32, vcc
	v_cndmask_b32_e32 v33, 0, v33, vcc
	v_lshlrev_b32_e32 v48, 16, v14
	v_and_b32_e32 v49, s22, v14
	v_mul_f32_e32 v50, s23, v48
	v_mul_f32_e32 v51, s23, v49
	v_exp_f32_e32 v50, v50
	v_exp_f32_e32 v51, v51
	v_lshlrev_b32_e32 v34, 16, v18
	v_and_b32_e32 v35, s22, v18
	v_lshlrev_b32_e32 v36, 16, v22
	v_and_b32_e32 v37, s22, v22
	v_lshlrev_b32_e32 v38, 16, v6
	v_and_b32_e32 v39, s22, v6
	v_lshlrev_b32_e32 v40, 16, v10
	v_and_b32_e32 v41, s22, v10
	v_lshlrev_b32_e32 v42, 16, v26
	v_and_b32_e32 v43, s22, v26
	v_lshlrev_b32_e32 v44, 16, v30
	v_and_b32_e32 v45, s22, v30
	v_lshlrev_b32_e32 v46, 16, v2
	v_and_b32_e32 v47, s22, v2
	v_pk_mul_f32 v[34:35], v[34:35], v[36:37]
	v_pk_mul_f32 v[38:39], v[38:39], v[40:41]
	v_pk_mul_f32 v[42:43], v[42:43], v[44:45]
	v_pk_mul_f32 v[34:35], v[34:35], v[196:197]
	v_pk_add_f32 v[50:51], v[50:51], 1.0 op_sel_hi:[1,0]
	v_pk_fma_f32 v[34:35], v[38:39], v[204:205], v[34:35]
	s_nop 0
	v_pk_fma_f32 v[34:35], v[42:43], v[212:213], v[34:35]
	s_nop 0
	v_pk_mul_f32 v[34:35], v[34:35], v[46:47]
	v_div_scale_f32 v52, s[0:1], v51, v51, v49
	v_rcp_f32_e32 v53, v52
	s_nop 0
	v_fma_f32 v54, -v52, v53, 1.0
	v_fmac_f32_e32 v53, v54, v53
	v_div_scale_f32 v54, vcc, v49, v51, v49
	v_mul_f32_e32 v55, v54, v53
	v_fma_f32 v56, -v52, v55, v54
	v_fmac_f32_e32 v55, v56, v53
	v_fma_f32 v52, -v52, v55, v54
	v_div_fmas_f32 v52, v52, v53, v55
	v_div_fixup_f32 v51, v52, v51, v49
	v_div_scale_f32 v52, s[0:1], v50, v50, v48
	v_rcp_f32_e32 v53, v52
	s_nop 0
	v_fma_f32 v54, -v52, v53, 1.0
	v_fmac_f32_e32 v53, v54, v53
	v_div_scale_f32 v54, vcc, v48, v50, v48
	v_mul_f32_e32 v55, v54, v53
	v_fma_f32 v56, -v52, v55, v54
	v_fmac_f32_e32 v55, v56, v53
	v_fma_f32 v52, -v52, v55, v54
	v_div_fmas_f32 v52, v52, v53, v55
	v_div_fixup_f32 v50, v52, v50, v48
	s_nop 0
	v_pk_mul_f32 v[34:35], v[50:51], v[34:35]
	s_nop 0
	v_cvt_pk_bf16_f32 v62, v34, v35
	v_lshlrev_b32_e32 v48, 16, v15
	v_and_b32_e32 v49, s22, v15
	v_mul_f32_e32 v50, s23, v48
	v_mul_f32_e32 v51, s23, v49
	v_exp_f32_e32 v50, v50
	v_exp_f32_e32 v51, v51
	v_lshlrev_b32_e32 v34, 16, v19
	v_and_b32_e32 v35, s22, v19
	v_lshlrev_b32_e32 v36, 16, v23
	v_and_b32_e32 v37, s22, v23
	v_lshlrev_b32_e32 v38, 16, v7
	v_and_b32_e32 v39, s22, v7
	v_lshlrev_b32_e32 v40, 16, v11
	v_and_b32_e32 v41, s22, v11
	v_lshlrev_b32_e32 v42, 16, v27
	v_and_b32_e32 v43, s22, v27
	v_lshlrev_b32_e32 v44, 16, v31
	v_and_b32_e32 v45, s22, v31
	v_lshlrev_b32_e32 v46, 16, v3
	v_and_b32_e32 v47, s22, v3
	v_pk_mul_f32 v[34:35], v[34:35], v[36:37]
	v_pk_mul_f32 v[38:39], v[38:39], v[40:41]
	v_pk_mul_f32 v[42:43], v[42:43], v[44:45]
	v_pk_mul_f32 v[34:35], v[34:35], v[198:199]
	v_pk_add_f32 v[50:51], v[50:51], 1.0 op_sel_hi:[1,0]
	v_pk_fma_f32 v[34:35], v[38:39], v[206:207], v[34:35]
	s_nop 0
	v_pk_fma_f32 v[34:35], v[42:43], v[214:215], v[34:35]
	s_nop 0
	v_pk_mul_f32 v[34:35], v[34:35], v[46:47]
	v_div_scale_f32 v52, s[0:1], v51, v51, v49
	v_rcp_f32_e32 v53, v52
	s_nop 0
	v_fma_f32 v54, -v52, v53, 1.0
	v_fmac_f32_e32 v53, v54, v53
	v_div_scale_f32 v54, vcc, v49, v51, v49
	v_mul_f32_e32 v55, v54, v53
	v_fma_f32 v56, -v52, v55, v54
	v_fmac_f32_e32 v55, v56, v53
	v_fma_f32 v52, -v52, v55, v54
	v_div_fmas_f32 v52, v52, v53, v55
	v_div_fixup_f32 v51, v52, v51, v49
	v_div_scale_f32 v52, s[0:1], v50, v50, v48
	v_rcp_f32_e32 v53, v52
	s_nop 0
	v_fma_f32 v54, -v52, v53, 1.0
	v_fmac_f32_e32 v53, v54, v53
	v_div_scale_f32 v54, vcc, v48, v50, v48
	v_mul_f32_e32 v55, v54, v53
	v_fma_f32 v56, -v52, v55, v54
	v_fmac_f32_e32 v55, v56, v53
	v_fma_f32 v52, -v52, v55, v54
	v_div_fmas_f32 v52, v52, v53, v55
	v_div_fixup_f32 v50, v52, v50, v48
	s_nop 0
	v_pk_mul_f32 v[34:35], v[50:51], v[34:35]
	s_nop 0
	v_cvt_pk_bf16_f32 v63, v34, v35
	v_lshlrev_b32_e32 v48, 16, v16
	v_and_b32_e32 v49, s22, v16
	v_mul_f32_e32 v50, s23, v48
	v_mul_f32_e32 v51, s23, v49
	v_exp_f32_e32 v50, v50
	v_exp_f32_e32 v51, v51
	v_lshlrev_b32_e32 v34, 16, v20
	v_and_b32_e32 v35, s22, v20
	v_lshlrev_b32_e32 v36, 16, v24
	v_and_b32_e32 v37, s22, v24
	v_lshlrev_b32_e32 v38, 16, v8
	v_and_b32_e32 v39, s22, v8
	v_lshlrev_b32_e32 v40, 16, v12
	v_and_b32_e32 v41, s22, v12
	v_lshlrev_b32_e32 v42, 16, v28
	v_and_b32_e32 v43, s22, v28
	v_lshlrev_b32_e32 v44, 16, v32
	v_and_b32_e32 v45, s22, v32
	v_lshlrev_b32_e32 v46, 16, v4
	v_and_b32_e32 v47, s22, v4
	v_pk_mul_f32 v[34:35], v[34:35], v[36:37]
	v_pk_mul_f32 v[38:39], v[38:39], v[40:41]
	v_pk_mul_f32 v[42:43], v[42:43], v[44:45]
	v_pk_mul_f32 v[34:35], v[34:35], v[200:201]
	v_pk_add_f32 v[50:51], v[50:51], 1.0 op_sel_hi:[1,0]
	v_pk_fma_f32 v[34:35], v[38:39], v[208:209], v[34:35]
	s_nop 0
	v_pk_fma_f32 v[34:35], v[42:43], v[216:217], v[34:35]
	s_nop 0
	v_pk_mul_f32 v[34:35], v[34:35], v[46:47]
	v_div_scale_f32 v52, s[0:1], v51, v51, v49
	v_rcp_f32_e32 v53, v52
	s_nop 0
	v_fma_f32 v54, -v52, v53, 1.0
	v_fmac_f32_e32 v53, v54, v53
	v_div_scale_f32 v54, vcc, v49, v51, v49
	v_mul_f32_e32 v55, v54, v53
	v_fma_f32 v56, -v52, v55, v54
	v_fmac_f32_e32 v55, v56, v53
	v_fma_f32 v52, -v52, v55, v54
	v_div_fmas_f32 v52, v52, v53, v55
	v_div_fixup_f32 v51, v52, v51, v49
	v_div_scale_f32 v52, s[0:1], v50, v50, v48
	v_rcp_f32_e32 v53, v52
	s_nop 0
	v_fma_f32 v54, -v52, v53, 1.0
	v_fmac_f32_e32 v53, v54, v53
	v_div_scale_f32 v54, vcc, v48, v50, v48
	v_mul_f32_e32 v55, v54, v53
	v_fma_f32 v56, -v52, v55, v54
	v_fmac_f32_e32 v55, v56, v53
	v_fma_f32 v52, -v52, v55, v54
	v_div_fmas_f32 v52, v52, v53, v55
	v_div_fixup_f32 v50, v52, v50, v48
	s_nop 0
	v_pk_mul_f32 v[34:35], v[50:51], v[34:35]
	s_nop 0
	v_cvt_pk_bf16_f32 v64, v34, v35
	v_lshlrev_b32_e32 v48, 16, v17
	v_and_b32_e32 v49, s22, v17
	v_mul_f32_e32 v50, s23, v48
	v_mul_f32_e32 v51, s23, v49
	v_exp_f32_e32 v50, v50
	v_exp_f32_e32 v51, v51
	v_lshlrev_b32_e32 v34, 16, v21
	v_and_b32_e32 v35, s22, v21
	v_lshlrev_b32_e32 v36, 16, v25
	v_and_b32_e32 v37, s22, v25
	v_lshlrev_b32_e32 v38, 16, v9
	v_and_b32_e32 v39, s22, v9
	v_lshlrev_b32_e32 v40, 16, v13
	v_and_b32_e32 v41, s22, v13
	v_lshlrev_b32_e32 v42, 16, v29
	v_and_b32_e32 v43, s22, v29
	v_lshlrev_b32_e32 v44, 16, v33
	v_and_b32_e32 v45, s22, v33
	v_lshlrev_b32_e32 v46, 16, v5
	v_and_b32_e32 v47, s22, v5
	v_pk_mul_f32 v[34:35], v[34:35], v[36:37]
	v_pk_mul_f32 v[38:39], v[38:39], v[40:41]
	v_pk_mul_f32 v[42:43], v[42:43], v[44:45]
	v_pk_mul_f32 v[34:35], v[34:35], v[202:203]
	v_pk_add_f32 v[50:51], v[50:51], 1.0 op_sel_hi:[1,0]
	v_pk_fma_f32 v[34:35], v[38:39], v[210:211], v[34:35]
	s_nop 0
	v_pk_fma_f32 v[34:35], v[42:43], v[218:219], v[34:35]
	s_nop 0
	v_pk_mul_f32 v[34:35], v[34:35], v[46:47]
	v_div_scale_f32 v52, s[0:1], v51, v51, v49
	v_rcp_f32_e32 v53, v52
	s_nop 0
	v_fma_f32 v54, -v52, v53, 1.0
	v_fmac_f32_e32 v53, v54, v53
	v_div_scale_f32 v54, vcc, v49, v51, v49
	v_mul_f32_e32 v55, v54, v53
	v_fma_f32 v56, -v52, v55, v54
	v_fmac_f32_e32 v55, v56, v53
	v_fma_f32 v52, -v52, v55, v54
	v_div_fmas_f32 v52, v52, v53, v55
	v_div_fixup_f32 v51, v52, v51, v49
	v_div_scale_f32 v52, s[0:1], v50, v50, v48
	v_rcp_f32_e32 v53, v52
	s_nop 0
	v_fma_f32 v54, -v52, v53, 1.0
	v_fmac_f32_e32 v53, v54, v53
	v_div_scale_f32 v54, vcc, v48, v50, v48
	v_mul_f32_e32 v55, v54, v53
	v_fma_f32 v56, -v52, v55, v54
	v_fmac_f32_e32 v55, v56, v53
	v_fma_f32 v52, -v52, v55, v54
	v_div_fmas_f32 v52, v52, v53, v55
	v_div_fixup_f32 v50, v52, v50, v48
	s_nop 0
	v_pk_mul_f32 v[34:35], v[50:51], v[34:35]
	s_nop 0
	v_cvt_pk_bf16_f32 v65, v34, v35
	s_nop 0
	global_store_dwordx4 v61, v[62:65], s[8:9] offset:512
	v_add_u32_e32 v58, 0x800, v58
	s_sub_u32 s74, s74, 1
	s_cmp_eq_u32 s74, 0
	s_cbranch_scc1 .Lcv_done
	s_branch .Lcv_loop
.Lcv_done:
.LBB0_176:
	s_or_b64 exec, exec, s[4:5]
	s_lshl_b32 s78, s34, 2
	s_add_u32 s10, s76, 0xd900000
	s_addc_u32 s11, s77, 0
	s_add_u32 s74, s76, 0xdc00000
	s_addc_u32 s75, s77, 0
	s_cmpk_lt_i32 s58, 0x80
	v_readlane_b32 s4, v255, 18
	s_cselect_b64 s[0:1], -1, 0
	v_readlane_b32 s5, v255, 19
	s_and_b64 s[0:1], s[4:5], s[0:1]
	s_and_b64 vcc, exec, s[0:1]
	s_cbranch_vccz .LBB0_213
	s_and_b32 s1, s58, 4
	s_and_b32 s0, s58, 3
	s_cmp_eq_u32 s1, 0
	s_cselect_b64 s[4:5], -1, 0
	s_cmp_lg_u32 s1, 0
	s_cselect_b64 s[22:23], -1, 0
	s_mov_b64 s[44:45], -1
	s_and_b64 vcc, exec, s[22:23]
	s_cbranch_vccz .LBB0_179
	s_lshl_b32 s1, s0, 6
	s_or_b32 s30, s1, 0xb00
	s_mov_b64 s[44:45], 0

.LBB0_218:
	v_cmp_lt_i32_e32 vcc, s20, v114
	s_or_b64 s[0:1], s[42:43], vcc
	s_and_saveexec_b64 s[82:83], s[0:1]
	s_cbranch_execz .LBB0_217
	v_lshlrev_b32_e32 v96, 1, v84
	s_and_saveexec_b64 s[0:1], vcc
	s_xor_b64 s[84:85], exec, s[0:1]
	s_cbranch_execz .LBB0_225
	v_lshrrev_b32_e32 v0, 5, v110
	v_and_b32_e32 v0, 0x7fffff0, v0
	v_bfe_u32 v120, v114, 7, 2
	v_readlane_b32 s0, v255, 37
	v_bfe_u32 v115, v114, 1, 6
	v_mov_b64_e32 v[2:3], s[6:7]
	v_add3_u32 v0, s0, v0, v120
	v_lshlrev_b64 v[104:105], 16, v[0:1]
	v_add_u32_e32 v0, 0xfffffc00, v114
	v_lshrrev_b32_e32 v121, 9, v0
	v_lshlrev_b32_e32 v0, 5, v114
	v_and_or_b32 v116, v0, 32, v124
	v_lshl_add_u32 v122, v121, 12, v187
	v_lshlrev_b32_e32 v0, 6, v115
	v_or3_b32 v0, v122, v0, v116
	v_mov_b64_e32 v[94:95], v[0:1]
	v_mad_u64_u32 v[102:103], s[0:1], v0, s19, v[2:3]
	v_lshlrev_b32_e32 v0, 7, v120
	v_lshl_add_u64 v[2:3], v[102:103], 0, v[0:1]
	v_mov_b32_e32 v97, v1
	v_lshl_add_u64 v[2:3], v[2:3], 0, v[96:97]
	s_mov_b64 s[0:1], 0x1400
	v_lshl_add_u64 v[4:5], v[2:3], 0, s[0:1]
	v_add_co_u32_e32 v2, vcc, s61, v2
	v_mov_b32_e32 v123, 0
	s_nop 0
	v_addc_co_u32_e32 v3, vcc, 0, v3, vcc
	global_load_dwordx4 v[50:53], v[4:5], off offset:32
	global_load_dwordx4 v[54:57], v[4:5], off offset:64
	global_load_dwordx4 v[58:61], v[2:3], off offset:1024
	global_load_dwordx4 v[62:65], v[4:5], off offset:96
	v_cmp_lt_i32_e32 vcc, v178, v177
	s_mov_b32 s0, 16
	v_lshlrev_b32_e32 v100, 6, v120
	v_cndmask_b32_e32 v0, v176, v178, vcc
	v_mov_b32_e32 v101, v1
	v_lshlrev_b32_e32 v117, 2, v0
	v_mov_b32_e32 v118, 0xf149f2ca
	v_mov_b64_e32 v[106:107], v[92:93]
	v_mov_b64_e32 v[108:109], v[90:91]
	v_mov_b32_e32 v18, 0
	v_mov_b32_e32 v19, v123
	v_mov_b32_e32 v20, v123
	v_mov_b32_e32 v21, v123
	v_mov_b32_e32 v22, v123
	v_mov_b32_e32 v23, v123
	v_mov_b32_e32 v24, v123
	v_mov_b32_e32 v25, v123
	v_mov_b32_e32 v26, v123
	v_mov_b32_e32 v27, v123
	v_mov_b32_e32 v28, v123
	v_mov_b32_e32 v29, v123
	v_mov_b32_e32 v30, v123
	v_mov_b32_e32 v31, v123
	v_mov_b32_e32 v32, v123
	v_mov_b32_e32 v33, v123
	v_mov_b32_e32 v2, 0
	v_mov_b32_e32 v3, v123
	v_mov_b32_e32 v4, v123
	v_mov_b32_e32 v5, v123
	v_mov_b32_e32 v6, v123
	v_mov_b32_e32 v7, v123
	v_mov_b32_e32 v8, v123
	v_mov_b32_e32 v9, v123
	v_mov_b32_e32 v10, v123
	v_mov_b32_e32 v11, v123
	v_mov_b32_e32 v12, v123
	v_mov_b32_e32 v13, v123
	v_mov_b32_e32 v14, v123
	v_mov_b32_e32 v15, v123
	v_mov_b32_e32 v16, v123
	v_mov_b32_e32 v17, v123
	v_mov_b32_e32 v244, 0x1ffc
	ds_write_b32 v244, v186
	v_lshrrev_b32_e32 v244, 6, v174
	v_mul_u32_u24_e32 v244, 0x2600, v244
	v_add_u32_e32 v244, 0x2000, v244
	v_lshrrev_b32_e32 v245, 3, v176
	v_mul_u32_u24_e32 v245, 0x90, v245
	v_and_b32_e32 v195, 7, v176
	v_lshl_add_u32 v245, v195, 4, v245
	v_add_u32_e32 v245, v245, v244
	v_lshrrev_b32_e32 v246, 2, v176
	v_mul_u32_u24_e32 v246, 0x50, v246
	v_and_b32_e32 v195, 3, v176
	v_lshl_add_u32 v246, v195, 4, v246
	v_add_u32_e32 v246, v246, v244
	v_add_u32_e32 v246, 0x1200, v246
	v_mul_u32_u24_e32 v247, 0x90, v124
	v_lshl_add_u32 v247, v125, 4, v247
	v_add_u32_e32 v247, v247, v244
	v_mul_u32_u24_e32 v252, 0x50, v124
	v_lshl_add_u32 v252, v125, 3, v252
	v_add_u32_e32 v252, v252, v244
	v_add_u32_e32 v252, 0x1200, v252
	v_add_u32_e32 v253, 0xa00, v252
	v_lshlrev_b32_e32 v244, 4, v176
	v_add_u32_e32 v196, v104, v244
	v_add_u32_e32 v196, 0xe400000, v196
	v_add_u32_e32 v197, 0x400, v196
	v_add_u32_e32 v198, 0x800, v196
	v_add_u32_e32 v199, 0xc00, v196
	v_lshrrev_b32_e32 v244, 2, v176
	v_lshlrev_b32_e32 v195, 4, v195
	v_lshl_add_u32 v200, v244, 10, v195
	v_add_u32_e32 v200, v200, v104
	v_add_u32_e32 v200, 0xe600000, v200
	v_add_u32_e32 v201, 0x4000, v200
	v_add_u32_e32 v202, 0x8000, v200
	v_add_u32_e32 v203, 0xc000, v200
	v_sub_u32_e64 v208, v115, 4 clamp
	v_min_u32_e32 v208, 56, v208
	v_lshlrev_b32_e32 v208, 6, v208
	v_lshl_add_u32 v204, v121, 12, v208
	v_add_u32_e32 v204, 0x1000, v204
	v_lshrrev_b32_e32 v205, 3, v176
	v_add_u32_e32 v204, v204, v205
	v_mul_lo_u32 v204, v204, s19
	v_and_b32_e32 v205, 7, v176
	v_lshlrev_b32_e32 v205, 4, v205
	v_lshl_add_u32 v205, v120, 7, v205
	v_add_u32_e32 v204, v204, v205
	v_add_u32_e32 v204, 0x3d01600, v204
	v_and_b32_e32 v205, 32, v116
	v_mul_u32_u24_e32 v205, 0x1c00, v205
	v_add_u32_e32 v204, v204, v205
	v_add_u32_e32 v205, 0xe000, v204
	v_add_u32_e32 v206, 0x1c000, v204
	v_add_u32_e32 v207, 0x2a000, v204
	v_lshl_add_u32 v209, v121, 2, v120
	v_lshl_add_u32 v209, v209, 6, v244
	v_lshlrev_b32_e32 v209, 13, v209
	v_lshl_add_u32 v208, v208, 1, v209
	v_add_u32_e32 v208, v208, v195
	v_add_u32_e32 v208, 0xde00000, v208
	v_and_b32_e32 v209, 32, v116
	v_lshl_add_u32 v208, v209, 1, v208
	v_add_u32_e32 v209, 0x20000, v208
	v_add_u32_e32 v210, 0x40000, v208
	v_add_u32_e32 v211, 0x60000, v208
	global_load_dwordx4 v[212:215], v196, s[56:57]
	global_load_dwordx4 v[216:219], v197, s[56:57]
	global_load_dwordx4 v[220:223], v198, s[56:57]
	global_load_dwordx4 v[224:227], v199, s[56:57]
	global_load_dwordx4 v[228:231], v200, s[56:57]
	global_load_dwordx4 v[232:235], v201, s[56:57]
	global_load_dwordx4 v[236:239], v202, s[56:57]
	global_load_dwordx4 v[240:243], v203, s[56:57]
	v_add_u32_e32 v196, 0x1000, v196
	v_add_u32_e32 v197, 0x1000, v197
	v_add_u32_e32 v198, 0x1000, v198
	v_add_u32_e32 v199, 0x1000, v199
	v_add_u32_e32 v200, 64, v200
	v_add_u32_e32 v201, 64, v201
	v_add_u32_e32 v202, 64, v202
	v_add_u32_e32 v203, 64, v203
	s_waitcnt vmcnt(0)
	ds_write_b128 v245, v[212:215]
	ds_write_b128 v245, v[216:219] offset:1152
	ds_write_b128 v245, v[220:223] offset:2304
	ds_write_b128 v245, v[224:227] offset:3456
	ds_write_b128 v246, v[228:231]
	ds_write_b128 v246, v[232:235] offset:1280
	ds_write_b128 v246, v[236:239] offset:2560
	ds_write_b128 v246, v[240:243] offset:3840
	s_waitcnt lgkmcnt(0)
	global_load_dwordx4 v[212:215], v196, s[56:57]
	global_load_dwordx4 v[216:219], v197, s[56:57]
	global_load_dwordx4 v[220:223], v198, s[56:57]
	global_load_dwordx4 v[224:227], v199, s[56:57]
	global_load_dwordx4 v[228:231], v200, s[56:57]
	global_load_dwordx4 v[232:235], v201, s[56:57]
	global_load_dwordx4 v[236:239], v202, s[56:57]
	global_load_dwordx4 v[240:243], v203, s[56:57]
	v_add_u32_e32 v196, 0x1000, v196
	v_add_u32_e32 v197, 0x1000, v197
	v_add_u32_e32 v198, 0x1000, v198
	v_add_u32_e32 v199, 0x1000, v199
	v_add_u32_e32 v200, 64, v200
	v_add_u32_e32 v201, 64, v201
	v_add_u32_e32 v202, 64, v202
	v_add_u32_e32 v203, 64, v203

.Lnb_ld_local:
	global_load_dwordx4 v[212:215], v204, s[56:57]
	global_load_dwordx4 v[216:219], v205, s[56:57]
	global_load_dwordx4 v[220:223], v206, s[56:57]
	global_load_dwordx4 v[224:227], v207, s[56:57]
	global_load_dwordx4 v[228:231], v208, s[56:57]
	global_load_dwordx4 v[232:235], v209, s[56:57]
	global_load_dwordx4 v[236:239], v210, s[56:57]
	global_load_dwordx4 v[240:243], v211, s[56:57]
	v_add_u32_e32 v204, 0x70000, v204
	v_add_u32_e32 v205, 0x70000, v205
	v_add_u32_e32 v206, 0x70000, v206
	v_add_u32_e32 v207, 0x70000, v207
	v_add_u32_e32 v208, 0x80, v208
	v_add_u32_e32 v209, 0x80, v209
	v_add_u32_e32 v210, 0x80, v210
	v_add_u32_e32 v211, 0x80, v211
.Lnb_ld_done:
	v_mul_f32_e32 v118, 0x3e38aa3b, v34
	v_mul_f32_e32 v119, 0x3e38aa3b, v35
	v_max3_f32 v118, v118, s52, v119
	v_mul_f32_e32 v119, 0x3e38aa3b, v36
	v_mul_f32_e32 v123, 0x3e38aa3b, v37
	v_max3_f32 v118, v118, v119, v123
	v_mul_f32_e32 v119, 0x3e38aa3b, v38
	v_mul_f32_e32 v123, 0x3e38aa3b, v39
	v_max3_f32 v118, v118, v119, v123
	v_mul_f32_e32 v119, 0x3e38aa3b, v40
	v_mul_f32_e32 v123, 0x3e38aa3b, v41
	v_max3_f32 v118, v118, v119, v123
	v_mul_f32_e32 v119, 0x3e38aa3b, v42
	v_mul_f32_e32 v123, 0x3e38aa3b, v43
	v_max3_f32 v118, v118, v119, v123
	v_mul_f32_e32 v119, 0x3e38aa3b, v44
	v_mul_f32_e32 v123, 0x3e38aa3b, v45
	v_max3_f32 v118, v118, v119, v123
	v_mul_f32_e32 v119, 0x3e38aa3b, v46
	v_mul_f32_e32 v123, 0x3e38aa3b, v47
	v_max3_f32 v118, v118, v119, v123
	v_mul_f32_e32 v119, 0x3e38aa3b, v48
	v_mul_f32_e32 v123, 0x3e38aa3b, v49
	v_max3_f32 v118, v118, v119, v123
	ds_bpermute_b32 v119, v117, v118
	s_waitcnt lgkmcnt(0)
	v_max3_f32 v118, v0, v118, v119
	v_fma_f32 v34, v34, s18, -v118
	v_exp_f32_e32 v34, v34
	v_fma_f32 v35, v35, s18, -v118
	v_exp_f32_e32 v35, v35
	v_fma_f32 v36, v36, s18, -v118
	v_exp_f32_e32 v36, v36
	v_fma_f32 v37, v37, s18, -v118
	v_exp_f32_e32 v37, v37
	v_fma_f32 v38, v38, s18, -v118
	v_add_f32_e32 v119, 0, v34
	v_exp_f32_e32 v38, v38
	v_fma_f32 v39, v39, s18, -v118
	v_sub_f32_e32 v0, v0, v118
	v_add_f32_e32 v119, v35, v119
	v_exp_f32_e32 v39, v39
	v_fma_f32 v40, v40, s18, -v118
	v_fma_f32 v41, v41, s18, -v118
	v_add_f32_e32 v119, v36, v119
	v_exp_f32_e32 v40, v40
	v_exp_f32_e32 v41, v41
	v_exp_f32_e32 v0, v0
	v_add_f32_e32 v119, v37, v119
	v_fma_f32 v42, v42, s18, -v118
	v_add_f32_e32 v119, v38, v119
	v_exp_f32_e32 v42, v42
	v_fma_f32 v43, v43, s18, -v118
	v_add_f32_e32 v119, v39, v119
	v_exp_f32_e32 v43, v43
	v_fma_f32 v44, v44, s18, -v118
	v_add_f32_e32 v119, v40, v119
	v_exp_f32_e32 v44, v44
	v_fma_f32 v45, v45, s18, -v118
	v_pk_mul_f32 v[32:33], v[32:33], v[0:1] op_sel_hi:[1,0]
	v_pk_mul_f32 v[30:31], v[30:31], v[0:1] op_sel_hi:[1,0]
	v_pk_mul_f32 v[28:29], v[28:29], v[0:1] op_sel_hi:[1,0]
	v_pk_mul_f32 v[26:27], v[26:27], v[0:1] op_sel_hi:[1,0]
	v_pk_mul_f32 v[24:25], v[24:25], v[0:1] op_sel_hi:[1,0]
	v_pk_mul_f32 v[22:23], v[22:23], v[0:1] op_sel_hi:[1,0]
	v_pk_mul_f32 v[20:21], v[20:21], v[0:1] op_sel_hi:[1,0]
	v_pk_mul_f32 v[18:19], v[18:19], v[0:1] op_sel_hi:[1,0]
	v_pk_mul_f32 v[16:17], v[16:17], v[0:1] op_sel_hi:[1,0]
	v_pk_mul_f32 v[14:15], v[14:15], v[0:1] op_sel_hi:[1,0]
	v_pk_mul_f32 v[12:13], v[12:13], v[0:1] op_sel_hi:[1,0]
	v_pk_mul_f32 v[10:11], v[10:11], v[0:1] op_sel_hi:[1,0]
	v_pk_mul_f32 v[8:9], v[8:9], v[0:1] op_sel_hi:[1,0]
	v_pk_mul_f32 v[6:7], v[6:7], v[0:1] op_sel_hi:[1,0]
	v_pk_mul_f32 v[4:5], v[4:5], v[0:1] op_sel_hi:[1,0]
	v_pk_mul_f32 v[2:3], v[2:3], v[0:1] op_sel_hi:[1,0]
	v_cvt_pk_bf16_f32 v34, v34, v35
	v_cvt_pk_bf16_f32 v35, v36, v37
	v_cvt_pk_bf16_f32 v36, v38, v39
	v_cvt_pk_bf16_f32 v37, v40, v41
	v_add_f32_e32 v119, v41, v119
	v_exp_f32_e32 v45, v45
	v_fma_f32 v46, v46, s18, -v118
	s_nop 0
	v_mfma_f32_32x32x16_bf16 v[18:33], v[78:81], v[34:37], v[18:33]
	v_add_f32_e32 v119, v42, v119
	v_exp_f32_e32 v46, v46
	v_fma_f32 v47, v47, s18, -v118
	v_add_f32_e32 v119, v43, v119
	v_exp_f32_e32 v47, v47
	v_fma_f32 v48, v48, s18, -v118
	v_fma_f32 v49, v49, s18, -v118
	s_nop 0
	v_mfma_f32_32x32x16_bf16 v[2:17], v[74:77], v[34:37], v[2:17]
	v_add_f32_e32 v119, v44, v119
	v_exp_f32_e32 v48, v48
	v_exp_f32_e32 v49, v49
	v_add_f32_e32 v119, v45, v119
	v_add_f32_e32 v119, v46, v119
	v_add_f32_e32 v119, v47, v119
	v_add_f32_e32 v119, v48, v119
	v_cvt_pk_bf16_f32 v34, v42, v43
	v_cvt_pk_bf16_f32 v35, v44, v45
	v_cvt_pk_bf16_f32 v36, v46, v47
	v_cvt_pk_bf16_f32 v37, v48, v49
	v_add_f32_e32 v119, v49, v119
	ds_bpermute_b32 v123, v117, v119
	v_mfma_f32_32x32x16_bf16 v[18:33], v[70:73], v[34:37], v[18:33]
	s_waitcnt lgkmcnt(0)
	v_add_f32_e32 v123, v119, v123
	v_fmac_f32_e32 v123, v97, v0
	v_mfma_f32_32x32x16_bf16 v[2:17], v[66:69], v[34:37], v[2:17]
	s_cmp_eq_u32 s0, 0
	s_cbranch_scc0 .LBB0_221
	v_sub_u32_e64 v0, v115, 4 clamp
	v_min_u32_e32 v105, 56, v0
	v_max_i32_e32 v0, 8, v116
	v_add_u32_e32 v0, -8, v0
	v_min_u32_e32 v119, 48, v0
	v_lshlrev_b32_e32 v0, 8, v121
	v_or3_b32 v0, v0, v100, v124
	s_movk_i32 s0, 0x744
	v_lshlrev_b64 v[34:35], 13, v[0:1]
	v_mad_u32_u24 v104, v120, s0, 0
	v_or_b32_e32 v120, v122, v124
	v_lshl_add_u64 v[106:107], v[86:87], 0, v[34:35]
	v_add_u32_e32 v121, 16, v119
	s_mov_b32 s0, 0
	s_mov_b32 s1, 0
	v_and_b32_e32 v36, 32, v116
	v_mul_u32_u24_e32 v37, 0x2300, v36
	v_sub_u32_e32 v196, v204, v37
	v_add_u32_e32 v196, 0xfff58000, v196
	v_add_u32_e32 v197, 0x70000, v196
	v_add_u32_e32 v198, 0xe0000, v196
	v_add_u32_e32 v199, 0x150000, v196
	v_and_b32_e32 v37, 3, v176
	v_mul_u32_u24_e32 v37, 0x70, v37
	v_add_u32_e32 v200, v208, v37
	v_lshrrev_b32_e32 v37, 5, v36
	v_mul_u32_u24_e32 v37, 0x50, v37
	v_sub_u32_e32 v200, v200, v37
	v_add_u32_e32 v200, 0xffffff40, v200
	v_add_u32_e32 v201, 0x20000, v200
	v_add_u32_e32 v202, 0x40000, v200
	v_add_u32_e32 v203, 0x60000, v200
.LBB0_223:
	v_add_u32_e32 v0, s1, v105
	v_sub_u32_e32 v0, v0, v115
	s_movk_i32 s4, 0x7c
	v_mad_u64_u32 v[108:109], s[4:5], v0, s4, v[104:105]
	v_lshlrev_b32_e32 v0, 1, v100
	v_and_b32_e32 v109, 32, v116
	v_or_b32_e32 v109, v109, v82
	v_mov_b32_e32 v122, v123
	v_sub_u32_e32 v36, v109, v119
	v_sub_u32_e32 v37, v109, v116
	v_add_u32_e32 v37, 15, v37
	v_lshl_add_u32 v108, v37, 2, v108
	v_mov_b32_e32 v37, 0x1c98
	v_cmp_gt_u32_e32 vcc, 16, v36
	v_mov_b32_e32 v162, v108
	s_nop 0
	v_cndmask_b32_e32 v162, v37, v162, vcc
	ds_read_b32 v162, v162 offset:868
	v_add_u32_e32 v35, 1, v36
	v_cmp_gt_u32_e32 vcc, 16, v35
	v_add_u32_e32 v163, 4, v108
	s_nop 0
	v_cndmask_b32_e32 v163, v37, v163, vcc
	ds_read_b32 v163, v163 offset:868
	v_add_u32_e32 v35, 2, v36
	v_cmp_gt_u32_e32 vcc, 16, v35
	v_add_u32_e32 v164, 8, v108
	s_nop 0
	v_cndmask_b32_e32 v164, v37, v164, vcc
	ds_read_b32 v164, v164 offset:868
	v_add_u32_e32 v35, 3, v36
	v_cmp_gt_u32_e32 vcc, 16, v35
	v_add_u32_e32 v165, 12, v108
	s_nop 0
	v_cndmask_b32_e32 v165, v37, v165, vcc
	ds_read_b32 v165, v165 offset:868
	v_add_u32_e32 v35, 8, v36
	v_cmp_gt_u32_e32 vcc, 16, v35
	v_add_u32_e32 v166, 32, v108
	s_nop 0
	v_cndmask_b32_e32 v166, v37, v166, vcc
	ds_read_b32 v166, v166 offset:868
	v_add_u32_e32 v35, 9, v36
	v_cmp_gt_u32_e32 vcc, 16, v35
	v_add_u32_e32 v167, 36, v108
	s_nop 0
	v_cndmask_b32_e32 v167, v37, v167, vcc
	ds_read_b32 v167, v167 offset:868
	v_add_u32_e32 v35, 10, v36
	v_cmp_gt_u32_e32 vcc, 16, v35
	v_add_u32_e32 v168, 40, v108
	s_nop 0
	v_cndmask_b32_e32 v168, v37, v168, vcc
	ds_read_b32 v168, v168 offset:868
	v_add_u32_e32 v35, 11, v36
	v_cmp_gt_u32_e32 vcc, 16, v35
	v_add_u32_e32 v169, 44, v108
	s_nop 0
	v_cndmask_b32_e32 v169, v37, v169, vcc
	ds_read_b32 v169, v169 offset:868
	v_add_u32_e32 v35, 16, v36
	v_cmp_gt_u32_e32 vcc, 16, v35
	v_add_u32_e32 v170, 64, v108
	s_nop 0
	v_cndmask_b32_e32 v170, v37, v170, vcc
	ds_read_b32 v170, v170 offset:868
	v_add_u32_e32 v35, 17, v36
	v_cmp_gt_u32_e32 vcc, 16, v35
	v_add_u32_e32 v171, 68, v108
	s_nop 0
	v_cndmask_b32_e32 v171, v37, v171, vcc
	ds_read_b32 v171, v171 offset:868
	v_add_u32_e32 v35, 18, v36
	v_cmp_gt_u32_e32 vcc, 16, v35
	v_add_u32_e32 v172, 72, v108
	s_nop 0
	v_cndmask_b32_e32 v172, v37, v172, vcc
	ds_read_b32 v172, v172 offset:868
	v_add_u32_e32 v35, 19, v36
	v_cmp_gt_u32_e32 vcc, 16, v35
	v_add_u32_e32 v173, 76, v108
	s_nop 0
	v_cndmask_b32_e32 v173, v37, v173, vcc
	ds_read_b32 v173, v173 offset:868
	v_add_u32_e32 v35, 24, v36
	v_cmp_gt_u32_e32 vcc, 16, v35
	v_add_u32_e32 v195, 96, v108
	s_nop 0
	v_cndmask_b32_e32 v195, v37, v195, vcc
	ds_read_b32 v195, v195 offset:868
	v_add_u32_e32 v35, 25, v36
	v_cmp_gt_u32_e32 vcc, 16, v35
	v_add_u32_e32 v244, 100, v108
	s_nop 0
	v_cndmask_b32_e32 v244, v37, v244, vcc
	ds_read_b32 v244, v244 offset:868
	v_add_u32_e32 v35, 26, v36
	v_cmp_gt_u32_e32 vcc, 16, v35
	v_add_u32_e32 v97, 104, v108
	s_nop 0
	v_cndmask_b32_e32 v97, v37, v97, vcc
	ds_read_b32 v97, v97 offset:868
	v_add_u32_e32 v35, 27, v36
	v_cmp_gt_u32_e32 vcc, 16, v35
	v_add_u32_e32 v123, 108, v108
	s_nop 0
	v_cndmask_b32_e32 v123, v37, v123, vcc
	ds_read_b32 v123, v123 offset:868
	s_add_i32 s1, s1, 1
	s_add_i32 s0, s0, 32
	ds_read_b128 v[248:251], v247
	ds_read_b128 v[126:129], v247 offset:32
	ds_read_b128 v[134:137], v247 offset:64
	ds_read_b128 v[138:141], v247 offset:96
	ds_read2_b64 v[78:81], v252 offset1:2
	ds_read2_b64 v[74:77], v253 offset1:2
	ds_read2_b64 v[70:73], v252 offset0:4 offset1:6
	ds_read2_b64 v[66:69], v253 offset0:4 offset1:6
	s_waitcnt vmcnt(0)
	ds_write_b128 v245, v[212:215]
	ds_write_b128 v245, v[216:219] offset:1152
	ds_write_b128 v245, v[220:223] offset:2304
	ds_write_b128 v245, v[224:227] offset:3456
	ds_write_b128 v246, v[228:231]
	ds_write_b128 v246, v[232:235] offset:1280
	ds_write_b128 v246, v[236:239] offset:2560
	ds_write_b128 v246, v[240:243] offset:3840
	s_waitcnt lgkmcnt(8)
	v_mfma_f32_32x32x16_bf16 v[34:49], v[248:251], v[58:61], 0
	v_mfma_f32_32x32x16_bf16 v[34:49], v[126:129], v[50:53], v[34:49]
	v_mfma_f32_32x32x16_bf16 v[34:49], v[134:137], v[54:57], v[34:49]
	v_mfma_f32_32x32x16_bf16 v[34:49], v[138:141], v[62:65], v[34:49]
	s_waitcnt lgkmcnt(0)
	s_cmp_ge_u32 s1, 7
	s_cbranch_scc1 .Lnb_l_skip
	global_load_dwordx4 v[212:215], v204, s[56:57]
	global_load_dwordx4 v[216:219], v205, s[56:57]
	global_load_dwordx4 v[220:223], v206, s[56:57]
	global_load_dwordx4 v[224:227], v207, s[56:57]
	global_load_dwordx4 v[228:231], v208, s[56:57]
	global_load_dwordx4 v[232:235], v209, s[56:57]
	global_load_dwordx4 v[236:239], v210, s[56:57]
	global_load_dwordx4 v[240:243], v211, s[56:57]
	v_add_u32_e32 v204, 0x70000, v204
	v_add_u32_e32 v205, 0x70000, v205
	v_add_u32_e32 v206, 0x70000, v206
	v_add_u32_e32 v207, 0x70000, v207
	v_add_u32_e32 v208, 0x80, v208
	v_add_u32_e32 v209, 0x80, v209
	v_add_u32_e32 v210, 0x80, v210
	v_add_u32_e32 v211, 0x80, v211
	s_branch .Lnb_l_cont
.Lnb_l_skip:
	global_load_dwordx4 v[212:215], v196, s[56:57]
	global_load_dwordx4 v[216:219], v197, s[56:57]
	global_load_dwordx4 v[220:223], v198, s[56:57]
	global_load_dwordx4 v[224:227], v199, s[56:57]
	global_load_dwordx4 v[228:231], v200, s[56:57]
	global_load_dwordx4 v[232:235], v201, s[56:57]
	global_load_dwordx4 v[236:239], v202, s[56:57]
	global_load_dwordx4 v[240:243], v203, s[56:57]
	v_add_u32_e32 v196, 0x1c0000, v196
	v_add_u32_e32 v197, 0x1c0000, v197
	v_add_u32_e32 v198, 0x1c0000, v198
	v_add_u32_e32 v199, 0x1c0000, v199
	v_add_u32_e32 v200, 0x200, v200
	v_add_u32_e32 v201, 0x200, v201
	v_add_u32_e32 v202, 0x200, v202
	v_add_u32_e32 v203, 0x200, v203
.Lnb_l_cont:
	v_fma_f32 v34, v34, s18, v162
	v_fma_f32 v35, v35, s18, v163
	v_fma_f32 v36, v36, s18, v164
	v_fma_f32 v37, v37, s18, v165
	v_fma_f32 v38, v38, s18, v166
	v_fma_f32 v39, v39, s18, v167
	v_fma_f32 v40, v40, s18, v168
	v_fma_f32 v41, v41, s18, v169
	v_fma_f32 v42, v42, s18, v170
	v_fma_f32 v43, v43, s18, v171
	v_fma_f32 v44, v44, s18, v172
	v_fma_f32 v45, v45, s18, v173
	v_fma_f32 v46, v46, s18, v195
	v_fma_f32 v47, v47, s18, v244
	v_fma_f32 v48, v48, s18, v97
	v_fma_f32 v49, v49, s18, v123
	v_max3_f32 v97, v34, s52, v35
	v_max3_f32 v97, v97, v36, v37
	v_max3_f32 v97, v97, v38, v39
	v_max3_f32 v97, v97, v40, v41
	v_max3_f32 v97, v97, v42, v43
	v_max3_f32 v97, v97, v44, v45
	v_max3_f32 v97, v97, v46, v47
	v_max3_f32 v97, v97, v48, v49
	s_cmp_eq_u32 s1, 8
	ds_bpermute_b32 v108, v117, v97
	s_waitcnt lgkmcnt(0)
	v_max3_f32 v97, v118, v97, v108
	v_sub_f32_e32 v34, v34, v97
	v_exp_f32_e32 v109, v34
	v_sub_f32_e32 v35, v35, v97
	v_exp_f32_e32 v35, v35
	v_sub_f32_e32 v36, v36, v97
	v_exp_f32_e32 v36, v36
	v_sub_f32_e32 v37, v37, v97
	v_exp_f32_e32 v37, v37
	v_sub_f32_e32 v38, v38, v97
	v_add_f32_e32 v34, 0, v109
	v_exp_f32_e32 v38, v38
	v_sub_f32_e32 v39, v39, v97
	v_add_f32_e32 v34, v35, v34
	v_exp_f32_e32 v39, v39
	v_sub_f32_e32 v40, v40, v97
	v_add_f32_e32 v34, v36, v34
	v_exp_f32_e32 v40, v40
	v_sub_f32_e32 v41, v41, v97
	v_add_f32_e32 v34, v37, v34
	v_exp_f32_e32 v41, v41
	v_sub_f32_e32 v42, v42, v97
	v_add_f32_e32 v34, v38, v34
	v_exp_f32_e32 v42, v42
	v_sub_f32_e32 v43, v43, v97
	v_add_f32_e32 v34, v39, v34
	v_exp_f32_e32 v43, v43
	v_sub_f32_e32 v44, v44, v97
	v_add_f32_e32 v34, v40, v34
	v_exp_f32_e32 v44, v44
	v_sub_f32_e32 v45, v45, v97
	v_add_f32_e32 v34, v41, v34
	v_exp_f32_e32 v45, v45
	v_sub_f32_e32 v46, v46, v97
	v_add_f32_e32 v34, v42, v34
	v_exp_f32_e32 v46, v46
	v_sub_f32_e32 v47, v47, v97
	v_add_f32_e32 v34, v43, v34
	v_exp_f32_e32 v47, v47
	v_sub_f32_e32 v48, v48, v97
	v_add_f32_e32 v34, v44, v34
	v_exp_f32_e32 v48, v48
	v_sub_f32_e32 v49, v49, v97
	v_add_f32_e32 v34, v45, v34
	v_exp_f32_e32 v49, v49
	v_add_f32_e32 v34, v46, v34
	v_add_f32_e32 v34, v47, v34
	v_add_f32_e32 v34, v48, v34
	v_sub_f32_e32 v108, v118, v97
	v_add_f32_e32 v118, v49, v34
	v_exp_f32_e32 v34, v108
	ds_bpermute_b32 v108, v117, v118
	v_pk_mul_f32 v[32:33], v[32:33], v[34:35] op_sel_hi:[1,0]
	v_pk_mul_f32 v[30:31], v[30:31], v[34:35] op_sel_hi:[1,0]
	s_waitcnt lgkmcnt(0)
	v_add_f32_e32 v123, v118, v108
	v_fmac_f32_e32 v123, v122, v34
	v_pk_mul_f32 v[28:29], v[28:29], v[34:35] op_sel_hi:[1,0]
	v_pk_mul_f32 v[26:27], v[26:27], v[34:35] op_sel_hi:[1,0]
	v_pk_mul_f32 v[24:25], v[24:25], v[34:35] op_sel_hi:[1,0]
	v_pk_mul_f32 v[22:23], v[22:23], v[34:35] op_sel_hi:[1,0]
	v_pk_mul_f32 v[20:21], v[20:21], v[34:35] op_sel_hi:[1,0]
	v_pk_mul_f32 v[18:19], v[18:19], v[34:35] op_sel_hi:[1,0]
	v_pk_mul_f32 v[16:17], v[16:17], v[34:35] op_sel_hi:[1,0]
	v_pk_mul_f32 v[14:15], v[14:15], v[34:35] op_sel_hi:[1,0]
	v_pk_mul_f32 v[12:13], v[12:13], v[34:35] op_sel_hi:[1,0]
	v_pk_mul_f32 v[10:11], v[10:11], v[34:35] op_sel_hi:[1,0]
	v_pk_mul_f32 v[8:9], v[8:9], v[34:35] op_sel_hi:[1,0]
	v_pk_mul_f32 v[6:7], v[6:7], v[34:35] op_sel_hi:[1,0]
	v_pk_mul_f32 v[4:5], v[4:5], v[34:35] op_sel_hi:[1,0]
	v_pk_mul_f32 v[2:3], v[2:3], v[34:35] op_sel_hi:[1,0]
	v_cvt_pk_bf16_f32 v34, v109, v35
	v_cvt_pk_bf16_f32 v35, v36, v37
	v_cvt_pk_bf16_f32 v36, v38, v39
	v_cvt_pk_bf16_f32 v37, v40, v41
	v_mov_b32_e32 v118, v97
	s_nop 0
	v_mfma_f32_32x32x16_bf16 v[18:33], v[78:81], v[34:37], v[18:33]
	s_nop 0
	v_mfma_f32_32x32x16_bf16 v[2:17], v[74:77], v[34:37], v[2:17]
	v_cvt_pk_bf16_f32 v34, v42, v43
	v_cvt_pk_bf16_f32 v35, v44, v45
	v_cvt_pk_bf16_f32 v36, v46, v47
	v_cvt_pk_bf16_f32 v37, v48, v49
	s_nop 1
	v_mfma_f32_32x32x16_bf16 v[18:33], v[70:73], v[34:37], v[18:33]
	s_nop 0
	v_mfma_f32_32x32x16_bf16 v[2:17], v[66:69], v[34:37], v[2:17]
	s_cbranch_scc0 .LBB0_223
.Lnb_far:
	s_sub_i32 s2, s1, 8
	s_lshl_b32 s2, s2, 2
	v_add_u32_e32 v0, s2, v105
	v_sub_u32_e32 v0, v0, v115
	s_movk_i32 s4, 0x7c
	v_mad_u64_u32 v[108:109], s[4:5], v0, s4, v[104:105]
	v_lshlrev_b32_e32 v0, 1, v100
	v_mov_b32_e32 v122, v123
	v_and_b32_e32 v36, 32, v116
	v_lshrrev_b32_e32 v36, 2, v36
	v_sub_u32_e32 v36, 32, v36
	v_add_u32_e32 v36, v36, v82
	v_sub_u32_e32 v37, v36, v116
	v_add_u32_e32 v37, 15, v37
	v_lshl_add_u32 v108, v37, 2, v108
	v_sub_u32_e32 v36, v36, v119
	v_mov_b32_e32 v37, 0x1c98
	v_cmp_gt_u32_e32 vcc, 16, v36
	v_mov_b32_e32 v162, v108
	s_nop 0
	v_cndmask_b32_e32 v162, v37, v162, vcc
	ds_read_b32 v162, v162 offset:868
	v_add_u32_e32 v35, 1, v36
	v_cmp_gt_u32_e32 vcc, 16, v35
	v_add_u32_e32 v163, 4, v108
	s_nop 0
	v_cndmask_b32_e32 v163, v37, v163, vcc
	ds_read_b32 v163, v163 offset:868
	v_add_u32_e32 v35, 2, v36
	v_cmp_gt_u32_e32 vcc, 16, v35
	v_add_u32_e32 v164, 8, v108
	s_nop 0
	v_cndmask_b32_e32 v164, v37, v164, vcc
	ds_read_b32 v164, v164 offset:868
	v_add_u32_e32 v35, 3, v36
	v_cmp_gt_u32_e32 vcc, 16, v35
	v_add_u32_e32 v165, 12, v108
	s_nop 0
	v_cndmask_b32_e32 v165, v37, v165, vcc
	ds_read_b32 v165, v165 offset:868
	v_cmp_gt_u32_e32 vcc, 16, v36
	v_add_u32_e32 v166, 124, v108
	s_nop 0
	v_cndmask_b32_e32 v166, v37, v166, vcc
	ds_read_b32 v166, v166 offset:868
	v_add_u32_e32 v35, 1, v36
	v_cmp_gt_u32_e32 vcc, 16, v35
	v_add_u32_e32 v167, 128, v108
	s_nop 0
	v_cndmask_b32_e32 v167, v37, v167, vcc
	ds_read_b32 v167, v167 offset:868
	v_add_u32_e32 v35, 2, v36
	v_cmp_gt_u32_e32 vcc, 16, v35
	v_add_u32_e32 v168, 132, v108
	s_nop 0
	v_cndmask_b32_e32 v168, v37, v168, vcc
	ds_read_b32 v168, v168 offset:868
	v_add_u32_e32 v35, 3, v36
	v_cmp_gt_u32_e32 vcc, 16, v35
	v_add_u32_e32 v169, 136, v108
	s_nop 0
	v_cndmask_b32_e32 v169, v37, v169, vcc
	ds_read_b32 v169, v169 offset:868
	v_cmp_gt_u32_e32 vcc, 16, v36
	v_add_u32_e32 v170, 248, v108
	s_nop 0
	v_cndmask_b32_e32 v170, v37, v170, vcc
	ds_read_b32 v170, v170 offset:868
	v_add_u32_e32 v35, 1, v36
	v_cmp_gt_u32_e32 vcc, 16, v35
	v_add_u32_e32 v171, 252, v108
	s_nop 0
	v_cndmask_b32_e32 v171, v37, v171, vcc
	ds_read_b32 v171, v171 offset:868
	v_add_u32_e32 v35, 2, v36
	v_cmp_gt_u32_e32 vcc, 16, v35
	v_add_u32_e32 v172, 256, v108
	s_nop 0
	v_cndmask_b32_e32 v172, v37, v172, vcc
	ds_read_b32 v172, v172 offset:868
	v_add_u32_e32 v35, 3, v36
	v_cmp_gt_u32_e32 vcc, 16, v35
	v_add_u32_e32 v173, 260, v108
	s_nop 0
	v_cndmask_b32_e32 v173, v37, v173, vcc
	ds_read_b32 v173, v173 offset:868
	v_cmp_gt_u32_e32 vcc, 16, v36
	v_add_u32_e32 v195, 372, v108
	s_nop 0
	v_cndmask_b32_e32 v195, v37, v195, vcc
	ds_read_b32 v195, v195 offset:868
	v_add_u32_e32 v35, 1, v36
	v_cmp_gt_u32_e32 vcc, 16, v35
	v_add_u32_e32 v244, 376, v108
	s_nop 0
	v_cndmask_b32_e32 v244, v37, v244, vcc
	ds_read_b32 v244, v244 offset:868
	v_add_u32_e32 v35, 2, v36
	v_cmp_gt_u32_e32 vcc, 16, v35
	v_add_u32_e32 v97, 380, v108
	s_nop 0
	v_cndmask_b32_e32 v97, v37, v97, vcc
	ds_read_b32 v97, v97 offset:868
	v_add_u32_e32 v35, 3, v36
	v_cmp_gt_u32_e32 vcc, 16, v35
	v_add_u32_e32 v123, 384, v108
	s_nop 0
	v_cndmask_b32_e32 v123, v37, v123, vcc
	ds_read_b32 v123, v123 offset:868
	s_add_i32 s1, s1, 1
	ds_read_b128 v[248:251], v247
	ds_read_b128 v[126:129], v247 offset:32
	ds_read_b128 v[134:137], v247 offset:64
	ds_read_b128 v[138:141], v247 offset:96
	ds_read2_b64 v[78:81], v252 offset1:2
	ds_read2_b64 v[74:77], v253 offset1:2
	ds_read2_b64 v[70:73], v252 offset0:4 offset1:6
	ds_read2_b64 v[66:69], v253 offset0:4 offset1:6
	s_waitcnt vmcnt(0)
	ds_write_b128 v245, v[212:215]
	ds_write_b128 v245, v[216:219] offset:1152
	ds_write_b128 v245, v[220:223] offset:2304
	ds_write_b128 v245, v[224:227] offset:3456
	ds_write_b128 v246, v[228:231]
	ds_write_b128 v246, v[232:235] offset:1280
	ds_write_b128 v246, v[236:239] offset:2560
	ds_write_b128 v246, v[240:243] offset:3840
	s_waitcnt lgkmcnt(8)
	v_mfma_f32_32x32x16_bf16 v[34:49], v[248:251], v[58:61], 0
	v_mfma_f32_32x32x16_bf16 v[34:49], v[126:129], v[50:53], v[34:49]
	v_mfma_f32_32x32x16_bf16 v[34:49], v[134:137], v[54:57], v[34:49]
	v_mfma_f32_32x32x16_bf16 v[34:49], v[138:141], v[62:65], v[34:49]
	s_waitcnt lgkmcnt(0)
	s_nop 9
	v_fma_f32 v34, v34, s18, v162
	v_fma_f32 v35, v35, s18, v163
	v_fma_f32 v36, v36, s18, v164
	v_fma_f32 v37, v37, s18, v165
	v_fma_f32 v38, v38, s18, v166
	v_fma_f32 v39, v39, s18, v167
	v_fma_f32 v40, v40, s18, v168
	v_fma_f32 v41, v41, s18, v169
	v_fma_f32 v42, v42, s18, v170
	v_fma_f32 v43, v43, s18, v171
	v_fma_f32 v44, v44, s18, v172
	v_fma_f32 v45, v45, s18, v173
	v_fma_f32 v46, v46, s18, v195
	v_fma_f32 v47, v47, s18, v244
	v_fma_f32 v48, v48, s18, v97
	v_fma_f32 v49, v49, s18, v123
	v_max3_f32 v97, v34, s52, v35
	v_max3_f32 v97, v97, v36, v37
	v_max3_f32 v97, v97, v38, v39
	v_max3_f32 v97, v97, v40, v41
	v_max3_f32 v97, v97, v42, v43
	v_max3_f32 v97, v97, v44, v45
	v_max3_f32 v97, v97, v46, v47
	v_max3_f32 v97, v97, v48, v49
	s_cmp_eq_u32 s1, 10
	ds_bpermute_b32 v108, v117, v97
	s_waitcnt lgkmcnt(0)
	v_max3_f32 v97, v118, v97, v108
	v_sub_f32_e32 v34, v34, v97
	v_exp_f32_e32 v109, v34
	v_sub_f32_e32 v35, v35, v97
	v_exp_f32_e32 v35, v35
	v_sub_f32_e32 v36, v36, v97
	v_exp_f32_e32 v36, v36
	v_sub_f32_e32 v37, v37, v97
	v_exp_f32_e32 v37, v37
	v_sub_f32_e32 v38, v38, v97
	v_add_f32_e32 v34, 0, v109
	v_exp_f32_e32 v38, v38
	v_sub_f32_e32 v39, v39, v97
	v_add_f32_e32 v34, v35, v34
	v_exp_f32_e32 v39, v39
	v_sub_f32_e32 v40, v40, v97
	v_add_f32_e32 v34, v36, v34
	v_exp_f32_e32 v40, v40
	v_sub_f32_e32 v41, v41, v97
	v_add_f32_e32 v34, v37, v34
	v_exp_f32_e32 v41, v41
	v_sub_f32_e32 v42, v42, v97
	v_add_f32_e32 v34, v38, v34
	v_exp_f32_e32 v42, v42
	v_sub_f32_e32 v43, v43, v97
	v_add_f32_e32 v34, v39, v34
	v_exp_f32_e32 v43, v43
	v_sub_f32_e32 v44, v44, v97
	v_add_f32_e32 v34, v40, v34
	v_exp_f32_e32 v44, v44
	v_sub_f32_e32 v45, v45, v97
	v_add_f32_e32 v34, v41, v34
	v_exp_f32_e32 v45, v45
	v_sub_f32_e32 v46, v46, v97
	v_add_f32_e32 v34, v42, v34
	v_exp_f32_e32 v46, v46
	v_sub_f32_e32 v47, v47, v97
	v_add_f32_e32 v34, v43, v34
	v_exp_f32_e32 v47, v47
	v_sub_f32_e32 v48, v48, v97
	v_add_f32_e32 v34, v44, v34
	v_exp_f32_e32 v48, v48
	v_sub_f32_e32 v49, v49, v97
	v_add_f32_e32 v34, v45, v34
	v_exp_f32_e32 v49, v49
	v_add_f32_e32 v34, v46, v34
	v_add_f32_e32 v34, v47, v34
	v_add_f32_e32 v34, v48, v34
	v_sub_f32_e32 v108, v118, v97
	v_add_f32_e32 v118, v49, v34
	v_exp_f32_e32 v34, v108
	ds_bpermute_b32 v108, v117, v118
	v_pk_mul_f32 v[32:33], v[32:33], v[34:35] op_sel_hi:[1,0]
	v_pk_mul_f32 v[30:31], v[30:31], v[34:35] op_sel_hi:[1,0]
	s_waitcnt lgkmcnt(0)
	v_add_f32_e32 v123, v118, v108
	v_fmac_f32_e32 v123, v122, v34
	v_pk_mul_f32 v[28:29], v[28:29], v[34:35] op_sel_hi:[1,0]
	v_pk_mul_f32 v[26:27], v[26:27], v[34:35] op_sel_hi:[1,0]
	v_pk_mul_f32 v[24:25], v[24:25], v[34:35] op_sel_hi:[1,0]
	v_pk_mul_f32 v[22:23], v[22:23], v[34:35] op_sel_hi:[1,0]
	v_pk_mul_f32 v[20:21], v[20:21], v[34:35] op_sel_hi:[1,0]
	v_pk_mul_f32 v[18:19], v[18:19], v[34:35] op_sel_hi:[1,0]
	v_pk_mul_f32 v[16:17], v[16:17], v[34:35] op_sel_hi:[1,0]
	v_pk_mul_f32 v[14:15], v[14:15], v[34:35] op_sel_hi:[1,0]
	v_pk_mul_f32 v[12:13], v[12:13], v[34:35] op_sel_hi:[1,0]
	v_pk_mul_f32 v[10:11], v[10:11], v[34:35] op_sel_hi:[1,0]
	v_pk_mul_f32 v[8:9], v[8:9], v[34:35] op_sel_hi:[1,0]
	v_pk_mul_f32 v[6:7], v[6:7], v[34:35] op_sel_hi:[1,0]
	v_pk_mul_f32 v[4:5], v[4:5], v[34:35] op_sel_hi:[1,0]
	v_pk_mul_f32 v[2:3], v[2:3], v[34:35] op_sel_hi:[1,0]
	v_cvt_pk_bf16_f32 v34, v109, v35
	v_cvt_pk_bf16_f32 v35, v36, v37
	v_cvt_pk_bf16_f32 v36, v38, v39
	v_cvt_pk_bf16_f32 v37, v40, v41
	v_mov_b32_e32 v118, v97
	s_nop 0
	v_mfma_f32_32x32x16_bf16 v[18:33], v[78:81], v[34:37], v[18:33]
	s_nop 0
	v_mfma_f32_32x32x16_bf16 v[2:17], v[74:77], v[34:37], v[2:17]
	v_cvt_pk_bf16_f32 v34, v42, v43
	v_cvt_pk_bf16_f32 v35, v44, v45
	v_cvt_pk_bf16_f32 v36, v46, v47
	v_cvt_pk_bf16_f32 v37, v48, v49
	s_nop 1
	v_mfma_f32_32x32x16_bf16 v[18:33], v[70:73], v[34:37], v[18:33]
	s_nop 0
	v_mfma_f32_32x32x16_bf16 v[2:17], v[66:69], v[34:37], v[2:17]
	s_cbranch_scc0 .Lnb_far
	v_lshl_add_u64 v[34:35], v[102:103], 0, v[0:1]
	s_mov_b64 s[0:1], 0x1a00
	v_lshl_add_u64 v[36:37], v[34:35], 0, s[0:1]
